# attend K rows and indexer K_idx blocks staged through wave-private LDS slots with fully coalesced loads (static LDS +20 KiB), dscan prefetch waits moved
# speedup vs baseline: 1.0847x; 1.0449x over previous
.LBB0_321:
	s_or_b64 exec, exec, s[0:1]
	s_add_i32 s10, 0, 0x22ff0
	s_mov_b64 s[0:1], src_shared_base
	s_cmp_lg_u32 s10, -1
	s_cselect_b32 s0, s10, 0
	s_cselect_b32 s1, s1, 0
	v_mov_b32_e32 v18, s0
	v_mov_b32_e32 v19, s1
	s_waitcnt lgkmcnt(0)
	s_barrier
	flat_load_dword v0, v[18:19] sc0 sc1
	s_waitcnt vmcnt(0)
	s_movk_i32 s0, 0x1040
	s_waitcnt lgkmcnt(0)
	v_cmp_gt_i32_e32 vcc, s0, v0
	s_mov_b64 s[0:1], -1
	s_mov_b64 s[2:3], exec
	v_writelane_b32 v253, s2, 40
	s_nop 1
	v_writelane_b32 v253, s3, 41
	s_and_b64 s[2:3], s[2:3], vcc
	s_mov_b64 exec, s[2:3]
	s_cbranch_execz .LBB0_318
	v_cmp_lt_i32_e64 s[18:19], 63, v0
	s_and_saveexec_b64 s[0:1], s[18:19]
	s_xor_b64 s[0:1], exec, s[0:1]
	v_subrev_u32_e32 v0, 64, v0
	v_lshrrev_b32_e32 v130, 9, v0
	v_not_b32_e32 v0, v0
	v_lshlrev_b32_e32 v0, 3, v0
	v_and_b32_e32 v18, 0xfc0, v0
	v_add_u32_e32 v139, 64, v18
	v_lshlrev_b32_e32 v18, 12, v130
	s_movk_i32 s2, 0xff8
	v_and_or_b32 v138, v0, s2, v18
	s_andn2_saveexec_b64 s[0:1], s[0:1]
	v_ashrrev_i32_e32 v130, 1, v0
	v_lshlrev_b32_e32 v0, 3, v0
	v_and_b32_e32 v0, 8, v0
	v_lshl_or_b32 v0, v130, 4, v0
	v_add_u32_e32 v138, 0x8000, v0
	v_mov_b32_e32 v139, 0x1010
	s_or_b64 exec, exec, s[0:1]
	s_movk_i32 s0, 0x100
	v_cmp_lt_u32_e32 vcc, s0, v139
	s_and_saveexec_b64 s[2:3], vcc
	s_cbranch_execz .LBB0_354
	s_cmp_eq_u64 s[18:19], exec
	s_cbranch_scc0 .Lix_skip
	v_readfirstlane_b32 s50, v138
	v_readfirstlane_b32 s51, v130
	v_readfirstlane_b32 s52, v139
	v_readfirstlane_b32 s53, v211
	v_readlane_b32 s42, v251, 15
	v_readlane_b32 s43, v251, 16
	s_lshr_b32 s53, s53, 6
	s_lshr_b32 s54, s52, 5
	s_sub_i32 s54, s54, s53
	s_add_i32 s54, s54, 7
	s_lshr_b32 s54, s54, 3
	s_lshl_b32 s56, s50, 10
	s_add_u32 s44, s42, s56
	s_addc_u32 s45, s43, 0
	s_add_u32 s44, s44, 0x8100000
	s_addc_u32 s45, s45, 0
	s_lshl_b32 s56, s50, 5
	s_add_u32 s46, s42, s56
	s_addc_u32 s47, s43, 0
	s_add_u32 s46, s46, 0x23e96200
	s_addc_u32 s47, s47, 0
	s_lshl_b32 s56, s51, 19
	s_lshl_b32 s57, s53, 12
	s_add_i32 s56, s56, s57
	s_add_u32 s48, s42, s56
	s_addc_u32 s49, s43, 0
	s_add_u32 s48, s48, 0x22982200
	s_addc_u32 s49, s49, 0
	s_mul_i32 s58, s53, 0xa00
	s_add_i32 s58, s58, 0x23000
	s_mov_b32 s55, 0
	v_and_b32_e32 v139, 15, v219
	v_lshrrev_b32_e32 v0, 4, v219
	v_lshlrev_b32_e32 v130, 4, v219
	v_and_b32_e32 v138, 7, v139
	v_lshlrev_b32_e32 v138, 10, v138
	v_lshrrev_b32_e32 v223, 3, v139
	v_lshl_add_u32 v138, v223, 7, v138
	v_lshl_add_u32 v138, v0, 4, v138
	global_load_dwordx4 v[94:97], v138, s[44:45] offset:0
	global_load_dwordx4 v[98:101], v138, s[44:45] offset:64
	global_load_dwordx4 v[102:105], v138, s[44:45] offset:256
	global_load_dwordx4 v[106:109], v138, s[44:45] offset:320
	global_load_dwordx4 v[110:113], v138, s[44:45] offset:512
	global_load_dwordx4 v[114:117], v138, s[44:45] offset:576
	global_load_dwordx4 v[118:121], v138, s[44:45] offset:768
	global_load_dwordx4 v[122:125], v138, s[44:45] offset:832
	v_and_b32_e32 v223, 1, v0
	v_lshlrev_b32_e32 v223, 7, v223
	v_lshrrev_b32_e32 v138, 1, v0
	v_lshl_add_u32 v223, v138, 2, v223
	global_load_dword v131, v223, s[46:47] offset:0
	global_load_dword v136, v223, s[46:47] offset:8
	global_load_dword v137, v223, s[46:47] offset:16
	global_load_dword v144, v223, s[46:47] offset:24
	global_load_dword v145, v223, s[46:47] offset:32
	global_load_dword v80, v223, s[46:47] offset:40
	global_load_dword v82, v223, s[46:47] offset:48
	global_load_dword v84, v223, s[46:47] offset:56
	global_load_dword v86, v223, s[46:47] offset:64
	global_load_dword v88, v223, s[46:47] offset:72
	global_load_dword v90, v223, s[46:47] offset:80
	global_load_dword v92, v223, s[46:47] offset:88
	global_load_dword v191, v223, s[46:47] offset:96
	global_load_dword v194, v223, s[46:47] offset:104
	global_load_dword v199, v223, s[46:47] offset:112
	global_load_dword v202, v223, s[46:47] offset:120
	global_load_dwordx4 v[52:55], v130, s[48:49] offset:0
	global_load_dwordx4 v[56:59], v130, s[48:49] offset:1024
	global_load_dwordx4 v[60:63], v130, s[48:49] offset:2048
	global_load_dwordx4 v[64:67], v130, s[48:49] offset:3072
	s_add_u32 s48, s48, 0x8000
	s_addc_u32 s49, s49, 0
	s_cmp_gt_u32 s54, 1
	s_cbranch_scc0 .Lix_pre1
	global_load_dwordx4 v[2:5], v130, s[48:49] offset:0
	global_load_dwordx4 v[6:9], v130, s[48:49] offset:1024
	global_load_dwordx4 v[10:13], v130, s[48:49] offset:2048
	global_load_dwordx4 v[14:17], v130, s[48:49] offset:3072
	s_add_u32 s48, s48, 0x8000
	s_addc_u32 s49, s49, 0
.Lix_pre1:
	s_cmp_gt_u32 s54, 2
	s_cbranch_scc0 .Lix_pre2
	global_load_dwordx4 v[68:71], v130, s[48:49] offset:0
	global_load_dwordx4 v[72:75], v130, s[48:49] offset:1024
	global_load_dwordx4 v[126:129], v130, s[48:49] offset:2048
	global_load_dwordx4 v[140:143], v130, s[48:49] offset:3072
	s_add_u32 s48, s48, 0x8000
	s_addc_u32 s49, s49, 0
.Lix_pre2:
	v_and_b32_e32 v138, 1, v0
	v_lshlrev_b32_e32 v138, 2, v138
	v_lshrrev_b32_e32 v223, 1, v0
	v_add_u32_e32 v138, v138, v223
	v_mul_u32_u24_e32 v138, 0x4050, v138
	v_lshl_add_u32 v138, v139, 2, v138
	s_lshl_b32 s56, s53, 7
	v_add_u32_e32 v138, s56, v138
	v_and_b32_e32 v223, 7, v139
	v_xor_b32_e32 v223, v223, v0
	v_lshlrev_b32_e32 v78, 4, v223
	v_lshl_add_u32 v78, v139, 7, v78
	v_add_u32_e32 v78, s58, v78
	v_xor_b32_e32 v223, 4, v223
	v_lshlrev_b32_e32 v223, 4, v223
	v_lshl_add_u32 v139, v139, 7, v223
	v_add_u32_e32 v139, s58, v139
	v_lshrrev_b32_e32 v0, 3, v219
	v_and_b32_e32 v223, 7, v219
	v_xor_b32_e32 v223, v223, v0
	v_lshlrev_b32_e32 v223, 4, v223
	v_lshl_add_u32 v223, v0, 7, v223
	v_add_u32_e32 v223, s58, v223
.Lix_loop:
	s_sub_i32 s56, s54, s55
	s_cmp_gt_u32 s56, 2
	s_cbranch_scc1 .Lix_w8_0
	s_waitcnt vmcnt(0)
	s_branch .Lix_go_0
.Lix_w8_0:
	s_waitcnt vmcnt(8)
.Lix_go_0:
	ds_write_b128 v223, v[52:55]
	ds_write_b128 v223, v[56:59] offset:1024
	ds_read_b128 v[226:229], v78
	ds_read_b128 v[230:233], v139
	ds_write_b128 v223, v[60:63]
	ds_write_b128 v223, v[64:67] offset:1024
	s_add_i32 s56, s55, 3
	s_cmp_lt_u32 s56, s54
	s_cbranch_scc0 .Lix_noiss_0
	global_load_dwordx4 v[52:55], v130, s[48:49] offset:0
	global_load_dwordx4 v[56:59], v130, s[48:49] offset:1024
	global_load_dwordx4 v[60:63], v130, s[48:49] offset:2048
	global_load_dwordx4 v[64:67], v130, s[48:49] offset:3072
	s_add_u32 s48, s48, 0x8000
	s_addc_u32 s49, s49, 0
.Lix_noiss_0:
	s_add_i32 s55, s55, 1
	s_waitcnt lgkmcnt(2)
	v_mfma_f32_16x16x32_bf16 v[20:23], v[94:97], v[226:229], 0
	v_mfma_f32_16x16x32_bf16 v[24:27], v[102:105], v[226:229], 0
	v_mfma_f32_16x16x32_bf16 v[28:31], v[110:113], v[226:229], 0
	v_mfma_f32_16x16x32_bf16 v[32:35], v[118:121], v[226:229], 0
	v_mfma_f32_16x16x32_bf16 v[20:23], v[98:101], v[230:233], v[20:23]
	v_mfma_f32_16x16x32_bf16 v[24:27], v[106:109], v[230:233], v[24:27]
	v_mfma_f32_16x16x32_bf16 v[28:31], v[114:117], v[230:233], v[28:31]
	v_mfma_f32_16x16x32_bf16 v[32:35], v[122:125], v[230:233], v[32:35]
	ds_read_b128 v[226:229], v78
	ds_read_b128 v[230:233], v139
	s_waitcnt lgkmcnt(0)
	v_mfma_f32_16x16x32_bf16 v[36:39], v[94:97], v[226:229], 0
	v_mfma_f32_16x16x32_bf16 v[40:43], v[102:105], v[226:229], 0
	v_mfma_f32_16x16x32_bf16 v[44:47], v[110:113], v[226:229], 0
	v_mfma_f32_16x16x32_bf16 v[48:51], v[118:121], v[226:229], 0
	v_mfma_f32_16x16x32_bf16 v[36:39], v[98:101], v[230:233], v[36:39]
	v_mfma_f32_16x16x32_bf16 v[40:43], v[106:109], v[230:233], v[40:43]
	v_mfma_f32_16x16x32_bf16 v[44:47], v[114:117], v[230:233], v[44:47]
	v_mfma_f32_16x16x32_bf16 v[48:51], v[122:125], v[230:233], v[48:51]
	v_max_f32_e32 v20, 0, v20
	v_max_f32_e32 v21, 0, v21
	v_max_f32_e32 v22, 0, v22
	v_max_f32_e32 v23, 0, v23
	v_mul_f32_e32 v20, v131, v20
	v_mul_f32_e32 v21, v145, v21
	v_mul_f32_e32 v22, v86, v22
	v_mul_f32_e32 v23, v191, v23
	v_max_f32_e32 v24, 0, v24
	v_max_f32_e32 v25, 0, v25
	v_max_f32_e32 v26, 0, v26
	v_max_f32_e32 v27, 0, v27
	v_fmac_f32_e32 v20, v136, v24
	v_fmac_f32_e32 v21, v80, v25
	v_fmac_f32_e32 v22, v88, v26
	v_fmac_f32_e32 v23, v194, v27
	v_max_f32_e32 v28, 0, v28
	v_max_f32_e32 v29, 0, v29
	v_max_f32_e32 v30, 0, v30
	v_max_f32_e32 v31, 0, v31
	v_fmac_f32_e32 v20, v137, v28
	v_fmac_f32_e32 v21, v82, v29
	v_fmac_f32_e32 v22, v90, v30
	v_fmac_f32_e32 v23, v199, v31
	v_max_f32_e32 v32, 0, v32
	v_max_f32_e32 v33, 0, v33
	v_max_f32_e32 v34, 0, v34
	v_max_f32_e32 v35, 0, v35
	v_fmac_f32_e32 v20, v144, v32
	v_fmac_f32_e32 v21, v84, v33
	v_fmac_f32_e32 v22, v92, v34
	v_fmac_f32_e32 v23, v202, v35
	s_nop 1
	v_permlane32_swap_b32_e32 v20, v21
	v_permlane32_swap_b32_e32 v22, v23
	v_add_f32_e32 v20, v20, v21
	v_add_f32_e32 v22, v22, v23
	ds_write_b32 v138, v20 offset:0
	ds_write_b32 v138, v22 offset:32928
	s_nop 1
	v_max_f32_e32 v36, 0, v36
	v_max_f32_e32 v37, 0, v37
	v_max_f32_e32 v38, 0, v38
	v_max_f32_e32 v39, 0, v39
	v_mul_f32_e32 v36, v131, v36
	v_mul_f32_e32 v37, v145, v37
	v_mul_f32_e32 v38, v86, v38
	v_mul_f32_e32 v39, v191, v39
	v_max_f32_e32 v40, 0, v40
	v_max_f32_e32 v41, 0, v41
	v_max_f32_e32 v42, 0, v42
	v_max_f32_e32 v43, 0, v43
	v_fmac_f32_e32 v36, v136, v40
	v_fmac_f32_e32 v37, v80, v41
	v_fmac_f32_e32 v38, v88, v42
	v_fmac_f32_e32 v39, v194, v43
	v_max_f32_e32 v44, 0, v44
	v_max_f32_e32 v45, 0, v45
	v_max_f32_e32 v46, 0, v46
	v_max_f32_e32 v47, 0, v47
	v_fmac_f32_e32 v36, v137, v44
	v_fmac_f32_e32 v37, v82, v45
	v_fmac_f32_e32 v38, v90, v46
	v_fmac_f32_e32 v39, v199, v47
	v_max_f32_e32 v48, 0, v48
	v_max_f32_e32 v49, 0, v49
	v_max_f32_e32 v50, 0, v50
	v_max_f32_e32 v51, 0, v51
	v_fmac_f32_e32 v36, v144, v48
	v_fmac_f32_e32 v37, v84, v49
	v_fmac_f32_e32 v38, v92, v50
	v_fmac_f32_e32 v39, v202, v51
	s_nop 1
	v_permlane32_swap_b32_e32 v36, v37
	v_permlane32_swap_b32_e32 v38, v39
	v_add_f32_e32 v36, v36, v37
	v_add_f32_e32 v38, v38, v39
	ds_write_b32 v138, v36 offset:64
	ds_write_b32 v138, v38 offset:32992
	v_add_u32_e32 v138, 0x400, v138
	s_cmp_ge_u32 s55, s54
	s_cbranch_scc1 .Lix_done
	s_sub_i32 s56, s54, s55
	s_cmp_gt_u32 s56, 2
	s_cbranch_scc1 .Lix_w8_1
	s_waitcnt vmcnt(0)
	s_branch .Lix_go_1

.Lix_go_1:
	ds_write_b128 v223, v[2:5]
	ds_write_b128 v223, v[6:9] offset:1024
	ds_read_b128 v[226:229], v78
	ds_read_b128 v[230:233], v139
	ds_write_b128 v223, v[10:13]
	ds_write_b128 v223, v[14:17] offset:1024
	s_add_i32 s56, s55, 3
	s_cmp_lt_u32 s56, s54
	s_cbranch_scc0 .Lix_noiss_1
	global_load_dwordx4 v[2:5], v130, s[48:49] offset:0
	global_load_dwordx4 v[6:9], v130, s[48:49] offset:1024
	global_load_dwordx4 v[10:13], v130, s[48:49] offset:2048
	global_load_dwordx4 v[14:17], v130, s[48:49] offset:3072
	s_add_u32 s48, s48, 0x8000
	s_addc_u32 s49, s49, 0

.Lix_go_2:
	ds_write_b128 v223, v[68:71]
	ds_write_b128 v223, v[72:75] offset:1024
	ds_read_b128 v[226:229], v78
	ds_read_b128 v[230:233], v139
	ds_write_b128 v223, v[126:129]
	ds_write_b128 v223, v[140:143] offset:1024
	s_add_i32 s56, s55, 3
	s_cmp_lt_u32 s56, s54
	s_cbranch_scc0 .Lix_noiss_2
	global_load_dwordx4 v[68:71], v130, s[48:49] offset:0
	global_load_dwordx4 v[72:75], v130, s[48:49] offset:1024
	global_load_dwordx4 v[126:129], v130, s[48:49] offset:2048
	global_load_dwordx4 v[140:143], v130, s[48:49] offset:3072
	s_add_u32 s48, s48, 0x8000
	s_addc_u32 s49, s49, 0
.Lix_noiss_2:
	s_add_i32 s55, s55, 1
	s_waitcnt lgkmcnt(2)
	v_mfma_f32_16x16x32_bf16 v[20:23], v[94:97], v[226:229], 0
	v_mfma_f32_16x16x32_bf16 v[24:27], v[102:105], v[226:229], 0
	v_mfma_f32_16x16x32_bf16 v[28:31], v[110:113], v[226:229], 0
	v_mfma_f32_16x16x32_bf16 v[32:35], v[118:121], v[226:229], 0
	v_mfma_f32_16x16x32_bf16 v[20:23], v[98:101], v[230:233], v[20:23]
	v_mfma_f32_16x16x32_bf16 v[24:27], v[106:109], v[230:233], v[24:27]
	v_mfma_f32_16x16x32_bf16 v[28:31], v[114:117], v[230:233], v[28:31]
	v_mfma_f32_16x16x32_bf16 v[32:35], v[122:125], v[230:233], v[32:35]
	ds_read_b128 v[226:229], v78
	ds_read_b128 v[230:233], v139
	s_waitcnt lgkmcnt(0)
	v_mfma_f32_16x16x32_bf16 v[36:39], v[94:97], v[226:229], 0
	v_mfma_f32_16x16x32_bf16 v[40:43], v[102:105], v[226:229], 0
	v_mfma_f32_16x16x32_bf16 v[44:47], v[110:113], v[226:229], 0
	v_mfma_f32_16x16x32_bf16 v[48:51], v[118:121], v[226:229], 0
	v_mfma_f32_16x16x32_bf16 v[36:39], v[98:101], v[230:233], v[36:39]
	v_mfma_f32_16x16x32_bf16 v[40:43], v[106:109], v[230:233], v[40:43]
	v_mfma_f32_16x16x32_bf16 v[44:47], v[114:117], v[230:233], v[44:47]
	v_mfma_f32_16x16x32_bf16 v[48:51], v[122:125], v[230:233], v[48:51]
	v_max_f32_e32 v20, 0, v20
	v_max_f32_e32 v21, 0, v21
	v_max_f32_e32 v22, 0, v22
	v_max_f32_e32 v23, 0, v23
	v_mul_f32_e32 v20, v131, v20
	v_mul_f32_e32 v21, v145, v21
	v_mul_f32_e32 v22, v86, v22
	v_mul_f32_e32 v23, v191, v23
	v_max_f32_e32 v24, 0, v24
	v_max_f32_e32 v25, 0, v25
	v_max_f32_e32 v26, 0, v26
	v_max_f32_e32 v27, 0, v27
	v_fmac_f32_e32 v20, v136, v24
	v_fmac_f32_e32 v21, v80, v25
	v_fmac_f32_e32 v22, v88, v26
	v_fmac_f32_e32 v23, v194, v27
	v_max_f32_e32 v28, 0, v28
	v_max_f32_e32 v29, 0, v29
	v_max_f32_e32 v30, 0, v30
	v_max_f32_e32 v31, 0, v31
	v_fmac_f32_e32 v20, v137, v28
	v_fmac_f32_e32 v21, v82, v29
	v_fmac_f32_e32 v22, v90, v30
	v_fmac_f32_e32 v23, v199, v31
	v_max_f32_e32 v32, 0, v32
	v_max_f32_e32 v33, 0, v33
	v_max_f32_e32 v34, 0, v34
	v_max_f32_e32 v35, 0, v35
	v_fmac_f32_e32 v20, v144, v32
	v_fmac_f32_e32 v21, v84, v33
	v_fmac_f32_e32 v22, v92, v34
	v_fmac_f32_e32 v23, v202, v35
	s_nop 1
	v_permlane32_swap_b32_e32 v20, v21
	v_permlane32_swap_b32_e32 v22, v23
	v_add_f32_e32 v20, v20, v21
	v_add_f32_e32 v22, v22, v23
	ds_write_b32 v138, v20 offset:0
	ds_write_b32 v138, v22 offset:32928
	s_nop 1
	v_max_f32_e32 v36, 0, v36
	v_max_f32_e32 v37, 0, v37
	v_max_f32_e32 v38, 0, v38
	v_max_f32_e32 v39, 0, v39
	v_mul_f32_e32 v36, v131, v36
	v_mul_f32_e32 v37, v145, v37
	v_mul_f32_e32 v38, v86, v38
	v_mul_f32_e32 v39, v191, v39
	v_max_f32_e32 v40, 0, v40
	v_max_f32_e32 v41, 0, v41
	v_max_f32_e32 v42, 0, v42
	v_max_f32_e32 v43, 0, v43
	v_fmac_f32_e32 v36, v136, v40
	v_fmac_f32_e32 v37, v80, v41
	v_fmac_f32_e32 v38, v88, v42
	v_fmac_f32_e32 v39, v194, v43
	v_max_f32_e32 v44, 0, v44
	v_max_f32_e32 v45, 0, v45
	v_max_f32_e32 v46, 0, v46
	v_max_f32_e32 v47, 0, v47
	v_fmac_f32_e32 v36, v137, v44
	v_fmac_f32_e32 v37, v82, v45
	v_fmac_f32_e32 v38, v90, v46
	v_fmac_f32_e32 v39, v199, v47
	v_max_f32_e32 v48, 0, v48
	v_max_f32_e32 v49, 0, v49
	v_max_f32_e32 v50, 0, v50
	v_max_f32_e32 v51, 0, v51
	v_fmac_f32_e32 v36, v144, v48
	v_fmac_f32_e32 v37, v84, v49
	v_fmac_f32_e32 v38, v92, v50
	v_fmac_f32_e32 v39, v202, v51
	s_nop 1
	v_permlane32_swap_b32_e32 v36, v37
	v_permlane32_swap_b32_e32 v38, v39
	v_add_f32_e32 v36, v36, v37
	v_add_f32_e32 v38, v38, v39
	ds_write_b32 v138, v36 offset:64
	ds_write_b32 v138, v38 offset:32992
	v_add_u32_e32 v138, 0x400, v138
	s_cmp_ge_u32 s55, s54
	s_cbranch_scc0 .Lix_loop
.Lix_done:
	v_mov_b32_e32 v130, s51
	v_mov_b32_e32 v138, s50
	v_mov_b32_e32 v139, s52
	s_branch .LBB0_354
.Lix_skip:
	v_add_u32_e32 v18, v138, v238
	v_ashrrev_i32_e32 v19, 31, v18
	v_lshlrev_b64 v[18:19], 10, v[18:19]
	v_lshl_add_u64 v[18:19], v[220:221], 0, v[18:19]
	flat_load_dwordx4 v[66:69], v[18:19]
	flat_load_dwordx4 v[70:73], v[18:19] offset:32
	flat_load_dwordx4 v[74:77], v[18:19] offset:64
	flat_load_dwordx4 v[78:81], v[18:19] offset:96
	flat_load_dwordx4 v[82:85], v[18:19] offset:512
	flat_load_dwordx4 v[86:89], v[18:19] offset:544
	flat_load_dwordx4 v[90:93], v[18:19] offset:576
	flat_load_dwordx4 v[94:97], v[18:19] offset:608
	v_add_u32_e32 v18, v138, v239
	v_ashrrev_i32_e32 v19, 31, v18
	v_readlane_b32 s0, v253, 18
	v_lshlrev_b64 v[18:19], 5, v[18:19]
	v_readlane_b32 s1, v253, 19
	v_add_u32_e32 v0, 31, v139
	v_lshrrev_b32_e32 v140, 5, v0
	v_lshl_add_u64 v[18:19], s[0:1], 0, v[18:19]
	flat_load_dwordx4 v[98:101], v[18:19]
	flat_load_dwordx4 v[102:105], v[18:19] offset:16
	flat_load_dwordx4 v[106:109], v[18:19] offset:32
	flat_load_dwordx4 v[110:113], v[18:19] offset:48
	flat_load_dwordx4 v[114:117], v[18:19] offset:64
	flat_load_dwordx4 v[118:121], v[18:19] offset:80
	flat_load_dwordx4 v[122:125], v[18:19] offset:96
	flat_load_dwordx4 v[126:129], v[18:19] offset:112
	v_cmp_lt_i32_e32 vcc, v237, v140
	s_and_saveexec_b64 s[20:21], vcc
	s_cbranch_execz .LBB0_337
	v_add_u32_e32 v0, -1, v139
	v_min_i32_e32 v2, v240, v0
	s_and_saveexec_b64 s[0:1], s[18:19]
	s_xor_b64 s[0:1], exec, s[0:1]
	s_cbranch_execz .LBB0_330
	v_ashrrev_i32_e32 v131, 31, v130
	v_readlane_b32 s22, v253, 20
	v_lshlrev_b64 v[4:5], 19, v[130:131]
	v_readlane_b32 s23, v253, 21
	v_ashrrev_i32_e32 v3, 31, v2
	s_nop 0
	v_lshl_add_u64 v[4:5], s[22:23], 0, v[4:5]

.LBB0_683:
	s_or_b64 exec, exec, s[0:1]
	s_waitcnt lgkmcnt(0)
	s_cmp_eq_u64 s[18:19], exec
	s_cbranch_scc0 .Lfa_skip
	v_readfirstlane_b32 s52, v223
	s_cmpk_eq_i32 s52, 0x100
	s_cbranch_scc0 .Lfa_skip
	v_readfirstlane_b32 s54, v211
	v_readfirstlane_b32 s57, v138
	v_readfirstlane_b32 s52, v130
	v_readlane_b32 s42, v251, 15
	v_readlane_b32 s43, v251, 16
	s_lshr_b32 s54, s54, 6
	s_add_i32 s57, s57, s54
	s_mul_i32 s55, s54, 0x4050
	s_mul_i32 s56, s54, 0x500
	s_add_i32 s56, s56, 0x20280
	s_lshl_b32 s52, s52, 20
	s_add_u32 s44, s42, s52
	s_addc_u32 s45, s43, 0
	s_add_u32 s46, s44, 0x22182200
	s_addc_u32 s47, s45, 0
	s_add_u32 s44, s44, 0x21982200
	s_addc_u32 s45, s45, 0
	s_lshl_b32 s52, s57, 10
	s_add_u32 s48, s42, s52
	s_addc_u32 s49, s43, 0
	s_add_u32 s50, s48, 0x1a580000
	s_addc_u32 s51, s49, 0
	s_add_u32 s48, s48, 0x6080000
	s_addc_u32 s49, s49, 0
	s_mov_b32 s70, 0x000f000f
	s_mov_b32 s71, 0x000f000f
	s_mov_b32 s58, 0x3e000000
	s_mov_b32 s59, 0x3e000000
	v_and_b32_e32 v202, 15, v219
	v_lshrrev_b32_e32 v223, 4, v219
	v_lshlrev_b32_e32 v194, 4, v202
	v_lshl_add_u32 v191, v223, 2, s56
	v_lshl_add_u32 v199, v202, 5, s55
	v_add_u32_e32 v142, 0, v223
	v_xor_b32_e32 v143, v202, v142
	v_lshlrev_b32_e32 v142, 8, v142
	v_lshl_add_u32 v142, v143, 4, v142
	v_add_u32_e32 v130, s55, v142
	v_add_u32_e32 v130, 0x3000, v130
	v_add_u32_e32 v142, 4, v223
	v_xor_b32_e32 v143, v202, v142
	v_lshlrev_b32_e32 v142, 8, v142
	v_lshl_add_u32 v142, v143, 4, v142
	v_add_u32_e32 v131, s55, v142
	v_add_u32_e32 v131, 0x3000, v131
	v_add_u32_e32 v142, 8, v223
	v_xor_b32_e32 v143, v202, v142
	v_lshlrev_b32_e32 v142, 8, v142
	v_lshl_add_u32 v142, v143, 4, v142
	v_add_u32_e32 v132, s55, v142
	v_add_u32_e32 v132, 0x3000, v132
	v_add_u32_e32 v142, 12, v223
	v_xor_b32_e32 v143, v202, v142
	v_lshlrev_b32_e32 v142, 8, v142
	v_lshl_add_u32 v142, v143, 4, v142
	v_add_u32_e32 v133, s55, v142
	v_add_u32_e32 v133, 0x3000, v133
	v_xor_b32_e32 v143, v202, v223
	v_xor_b32_e32 v142, 0, v143
	v_lshlrev_b32_e32 v142, 4, v142
	v_lshl_add_u32 v142, v202, 8, v142
	v_add_u32_e32 v134, s55, v142
	v_add_u32_e32 v134, 0x3000, v134
	v_xor_b32_e32 v142, 4, v143
	v_lshlrev_b32_e32 v142, 4, v142
	v_lshl_add_u32 v142, v202, 8, v142
	v_add_u32_e32 v135, s55, v142
	v_add_u32_e32 v135, 0x3000, v135
	v_xor_b32_e32 v142, 8, v143
	v_lshlrev_b32_e32 v142, 4, v142
	v_lshl_add_u32 v142, v202, 8, v142
	v_add_u32_e32 v136, s55, v142
	v_add_u32_e32 v136, 0x3000, v136
	v_xor_b32_e32 v142, 12, v143
	v_lshlrev_b32_e32 v142, 4, v142
	v_lshl_add_u32 v142, v202, 8, v142
	v_add_u32_e32 v137, s55, v142
	v_add_u32_e32 v137, 0x3000, v137
	v_mov_b32_e32 v2, 0
	v_mov_b32_e32 v3, 0
	v_mov_b32_e32 v4, 0
	v_mov_b32_e32 v5, 0
	v_mov_b32_e32 v6, 0
	v_mov_b32_e32 v7, 0
	v_mov_b32_e32 v8, 0
	v_mov_b32_e32 v9, 0
	v_mov_b32_e32 v10, 0
	v_mov_b32_e32 v11, 0
	v_mov_b32_e32 v12, 0
	v_mov_b32_e32 v13, 0
	v_mov_b32_e32 v14, 0
	v_mov_b32_e32 v15, 0
	v_mov_b32_e32 v16, 0
	v_mov_b32_e32 v17, 0
	v_lshlrev_b32_e32 v0, 7, v202
	v_lshl_add_u32 v0, v223, 4, v0
	s_mov_b64 exec, s[70:71]
	global_load_dwordx4 v[2:5], v0, s[48:49] offset:0
	global_load_dwordx4 v[6:9], v0, s[48:49] offset:64
	global_load_dwordx4 v[10:13], v0, s[48:49] offset:512
	global_load_dwordx4 v[14:17], v0, s[48:49] offset:576
	s_mov_b64 exec, -1
	ds_read2_b32 v[126:127], v191 offset0:0 offset1:4
	ds_read2_b32 v[128:129], v191 offset0:8 offset1:12
	s_waitcnt lgkmcnt(0)
	v_lshl_add_u32 v126, v126, 8, v194
	v_lshl_add_u32 v127, v127, 8, v194
	v_lshl_add_u32 v128, v128, 8, v194
	v_lshl_add_u32 v129, v129, 8, v194
	global_load_dwordx4 v[18:21], v126, s[44:45]
	global_load_dwordx4 v[22:25], v127, s[44:45]
	global_load_dwordx4 v[26:29], v128, s[44:45]
	global_load_dwordx4 v[30:33], v129, s[44:45]
	ds_read2_b32 v[126:127], v191 offset0:16 offset1:20
	ds_read2_b32 v[128:129], v191 offset0:24 offset1:28
	s_waitcnt lgkmcnt(0)
	v_lshl_add_u32 v126, v126, 8, v194
	v_lshl_add_u32 v127, v127, 8, v194
	v_lshl_add_u32 v128, v128, 8, v194
	v_lshl_add_u32 v129, v129, 8, v194
	global_load_dwordx4 v[34:37], v126, s[44:45]
	global_load_dwordx4 v[38:41], v127, s[44:45]
	global_load_dwordx4 v[42:45], v128, s[44:45]
	global_load_dwordx4 v[46:49], v129, s[44:45]
	ds_read2_b32 v[126:127], v191 offset0:32 offset1:36
	ds_read2_b32 v[128:129], v191 offset0:40 offset1:44
	s_waitcnt lgkmcnt(0)
	v_lshl_add_u32 v126, v126, 8, v194
	v_lshl_add_u32 v127, v127, 8, v194
	v_lshl_add_u32 v128, v128, 8, v194
	v_lshl_add_u32 v129, v129, 8, v194
	global_load_dwordx4 v[50:53], v126, s[44:45]
	global_load_dwordx4 v[54:57], v127, s[44:45]
	global_load_dwordx4 v[58:61], v128, s[44:45]
	global_load_dwordx4 v[62:65], v129, s[44:45]
	ds_read2_b32 v[126:127], v191 offset0:48 offset1:52
	ds_read2_b32 v[128:129], v191 offset0:56 offset1:60
	s_waitcnt lgkmcnt(0)
	v_lshl_add_u32 v126, v126, 8, v194
	v_lshl_add_u32 v127, v127, 8, v194
	v_lshl_add_u32 v128, v128, 8, v194
	v_lshl_add_u32 v129, v129, 8, v194
	global_load_dwordx4 v[94:97], v126, s[44:45]
	global_load_dwordx4 v[98:101], v127, s[44:45]
	global_load_dwordx4 v[102:105], v128, s[44:45]
	global_load_dwordx4 v[106:109], v129, s[44:45]
	ds_read2_b32 v[126:127], v191 offset0:64 offset1:68
	ds_read2_b32 v[128:129], v191 offset0:72 offset1:76
	s_waitcnt vmcnt(12)
	ds_write_b128 v130, v[18:21]
	ds_write_b128 v131, v[22:25]
	ds_write_b128 v132, v[26:29]
	ds_write_b128 v133, v[30:33]
	s_waitcnt lgkmcnt(4)
	v_lshl_add_u32 v126, v126, 8, v194
	v_lshl_add_u32 v127, v127, 8, v194
	v_lshl_add_u32 v128, v128, 8, v194
	v_lshl_add_u32 v129, v129, 8, v194
	global_load_dwordx4 v[18:21], v126, s[44:45]
	global_load_dwordx4 v[22:25], v127, s[44:45]
	global_load_dwordx4 v[26:29], v128, s[44:45]
	global_load_dwordx4 v[30:33], v129, s[44:45]
	ds_read_b128 v[110:113], v134
	ds_read_b128 v[114:117], v135
	ds_read_b128 v[118:121], v136
	ds_read_b128 v[122:125], v137
	ds_read2_b32 v[126:127], v191 offset0:80 offset1:84
	ds_read2_b32 v[128:129], v191 offset0:88 offset1:92
	s_waitcnt lgkmcnt(2)
	v_mfma_f32_16x16x32_bf16 v[66:69], v[2:5], v[110:113], 0
	v_mfma_f32_16x16x32_bf16 v[70:73], v[10:13], v[118:121], 0
	v_mfma_f32_16x16x32_bf16 v[66:69], v[6:9], v[114:117], v[66:69]
	v_mfma_f32_16x16x32_bf16 v[70:73], v[14:17], v[122:125], v[70:73]
	s_waitcnt vmcnt(12)
	ds_write_b128 v130, v[34:37]
	ds_write_b128 v131, v[38:41]
	ds_write_b128 v132, v[42:45]
	ds_write_b128 v133, v[46:49]
	s_waitcnt lgkmcnt(4)
	v_lshl_add_u32 v126, v126, 8, v194
	v_lshl_add_u32 v127, v127, 8, v194
	v_lshl_add_u32 v128, v128, 8, v194
	v_lshl_add_u32 v129, v129, 8, v194
	global_load_dwordx4 v[34:37], v126, s[44:45]
	global_load_dwordx4 v[38:41], v127, s[44:45]
	global_load_dwordx4 v[42:45], v128, s[44:45]
	global_load_dwordx4 v[46:49], v129, s[44:45]
	ds_read_b128 v[110:113], v134
	ds_read_b128 v[114:117], v135
	ds_read_b128 v[118:121], v136
	ds_read_b128 v[122:125], v137
	ds_read2_b32 v[126:127], v191 offset0:96 offset1:100
	ds_read2_b32 v[128:129], v191 offset0:104 offset1:108
	v_pk_mul_f32 v[66:67], v[66:67], s[58:59] op_sel_hi:[1,0]
	v_pk_mul_f32 v[68:69], v[68:69], s[58:59] op_sel_hi:[1,0]
	v_pk_mul_f32 v[70:71], v[70:71], s[58:59] op_sel_hi:[1,0]
	v_pk_mul_f32 v[72:73], v[72:73], s[58:59] op_sel_hi:[1,0]
	s_mov_b64 exec, 0xffff
	ds_write_b128 v199, v[66:69] offset:0
	ds_write_b128 v199, v[70:73] offset:16
	s_mov_b64 exec, -1
	s_waitcnt lgkmcnt(4)
	v_mfma_f32_16x16x32_bf16 v[226:229], v[2:5], v[110:113], 0
	v_mfma_f32_16x16x32_bf16 v[230:233], v[10:13], v[118:121], 0
	v_mfma_f32_16x16x32_bf16 v[226:229], v[6:9], v[114:117], v[226:229]
	v_mfma_f32_16x16x32_bf16 v[230:233], v[14:17], v[122:125], v[230:233]
	s_waitcnt vmcnt(12)
	ds_write_b128 v130, v[50:53]
	ds_write_b128 v131, v[54:57]
	ds_write_b128 v132, v[58:61]
	ds_write_b128 v133, v[62:65]
	s_waitcnt lgkmcnt(4)
	v_lshl_add_u32 v126, v126, 8, v194
	v_lshl_add_u32 v127, v127, 8, v194
	v_lshl_add_u32 v128, v128, 8, v194
	v_lshl_add_u32 v129, v129, 8, v194
	global_load_dwordx4 v[50:53], v126, s[44:45]
	global_load_dwordx4 v[54:57], v127, s[44:45]
	global_load_dwordx4 v[58:61], v128, s[44:45]
	global_load_dwordx4 v[62:65], v129, s[44:45]
	ds_read_b128 v[110:113], v134
	ds_read_b128 v[114:117], v135
	ds_read_b128 v[118:121], v136
	ds_read_b128 v[122:125], v137
	ds_read2_b32 v[126:127], v191 offset0:112 offset1:116
	ds_read2_b32 v[128:129], v191 offset0:120 offset1:124
	v_pk_mul_f32 v[226:227], v[226:227], s[58:59] op_sel_hi:[1,0]
	v_pk_mul_f32 v[228:229], v[228:229], s[58:59] op_sel_hi:[1,0]
	v_pk_mul_f32 v[230:231], v[230:231], s[58:59] op_sel_hi:[1,0]
	v_pk_mul_f32 v[232:233], v[232:233], s[58:59] op_sel_hi:[1,0]
	s_mov_b64 exec, 0xffff
	ds_write_b128 v199, v[226:229] offset:512
	ds_write_b128 v199, v[230:233] offset:528
	s_mov_b64 exec, -1
	s_waitcnt lgkmcnt(4)
	v_mfma_f32_16x16x32_bf16 v[66:69], v[2:5], v[110:113], 0
	v_mfma_f32_16x16x32_bf16 v[70:73], v[10:13], v[118:121], 0
	v_mfma_f32_16x16x32_bf16 v[66:69], v[6:9], v[114:117], v[66:69]
	v_mfma_f32_16x16x32_bf16 v[70:73], v[14:17], v[122:125], v[70:73]
	s_waitcnt vmcnt(12)
	ds_write_b128 v130, v[94:97]
	ds_write_b128 v131, v[98:101]
	ds_write_b128 v132, v[102:105]
	ds_write_b128 v133, v[106:109]
	s_waitcnt lgkmcnt(4)
	v_lshl_add_u32 v126, v126, 8, v194
	v_lshl_add_u32 v127, v127, 8, v194
	v_lshl_add_u32 v128, v128, 8, v194
	v_lshl_add_u32 v129, v129, 8, v194
	global_load_dwordx4 v[94:97], v126, s[44:45]
	global_load_dwordx4 v[98:101], v127, s[44:45]
	global_load_dwordx4 v[102:105], v128, s[44:45]
	global_load_dwordx4 v[106:109], v129, s[44:45]
	ds_read_b128 v[110:113], v134
	ds_read_b128 v[114:117], v135
	ds_read_b128 v[118:121], v136
	ds_read_b128 v[122:125], v137
	ds_read2_b32 v[126:127], v191 offset0:128 offset1:132
	ds_read2_b32 v[128:129], v191 offset0:136 offset1:140
	v_pk_mul_f32 v[66:67], v[66:67], s[58:59] op_sel_hi:[1,0]
	v_pk_mul_f32 v[68:69], v[68:69], s[58:59] op_sel_hi:[1,0]
	v_pk_mul_f32 v[70:71], v[70:71], s[58:59] op_sel_hi:[1,0]
	v_pk_mul_f32 v[72:73], v[72:73], s[58:59] op_sel_hi:[1,0]
	s_mov_b64 exec, 0xffff
	ds_write_b128 v199, v[66:69] offset:1056
	ds_write_b128 v199, v[70:73] offset:1072
	s_mov_b64 exec, -1
	s_waitcnt lgkmcnt(4)
	v_mfma_f32_16x16x32_bf16 v[226:229], v[2:5], v[110:113], 0
	v_mfma_f32_16x16x32_bf16 v[230:233], v[10:13], v[118:121], 0
	v_mfma_f32_16x16x32_bf16 v[226:229], v[6:9], v[114:117], v[226:229]
	v_mfma_f32_16x16x32_bf16 v[230:233], v[14:17], v[122:125], v[230:233]
	s_waitcnt vmcnt(12)
	ds_write_b128 v130, v[18:21]
	ds_write_b128 v131, v[22:25]
	ds_write_b128 v132, v[26:29]
	ds_write_b128 v133, v[30:33]
	s_waitcnt lgkmcnt(4)
	v_lshl_add_u32 v126, v126, 8, v194
	v_lshl_add_u32 v127, v127, 8, v194
	v_lshl_add_u32 v128, v128, 8, v194
	v_lshl_add_u32 v129, v129, 8, v194
	global_load_dwordx4 v[18:21], v126, s[44:45]
	global_load_dwordx4 v[22:25], v127, s[44:45]
	global_load_dwordx4 v[26:29], v128, s[44:45]
	global_load_dwordx4 v[30:33], v129, s[44:45]
	ds_read_b128 v[110:113], v134
	ds_read_b128 v[114:117], v135
	ds_read_b128 v[118:121], v136
	ds_read_b128 v[122:125], v137
	ds_read2_b32 v[126:127], v191 offset0:144 offset1:148
	ds_read2_b32 v[128:129], v191 offset0:152 offset1:156
	v_pk_mul_f32 v[226:227], v[226:227], s[58:59] op_sel_hi:[1,0]
	v_pk_mul_f32 v[228:229], v[228:229], s[58:59] op_sel_hi:[1,0]
	v_pk_mul_f32 v[230:231], v[230:231], s[58:59] op_sel_hi:[1,0]
	v_pk_mul_f32 v[232:233], v[232:233], s[58:59] op_sel_hi:[1,0]
	s_mov_b64 exec, 0xffff
	ds_write_b128 v199, v[226:229] offset:1568
	ds_write_b128 v199, v[230:233] offset:1584
	s_mov_b64 exec, -1
	s_waitcnt lgkmcnt(4)
	v_mfma_f32_16x16x32_bf16 v[66:69], v[2:5], v[110:113], 0
	v_mfma_f32_16x16x32_bf16 v[70:73], v[10:13], v[118:121], 0
	v_mfma_f32_16x16x32_bf16 v[66:69], v[6:9], v[114:117], v[66:69]
	v_mfma_f32_16x16x32_bf16 v[70:73], v[14:17], v[122:125], v[70:73]
	s_waitcnt vmcnt(12)
	ds_write_b128 v130, v[34:37]
	ds_write_b128 v131, v[38:41]
	ds_write_b128 v132, v[42:45]
	ds_write_b128 v133, v[46:49]
	s_waitcnt lgkmcnt(4)
	v_lshl_add_u32 v126, v126, 8, v194
	v_lshl_add_u32 v127, v127, 8, v194
	v_lshl_add_u32 v128, v128, 8, v194
	v_lshl_add_u32 v129, v129, 8, v194
	global_load_dwordx4 v[34:37], v126, s[44:45]
	global_load_dwordx4 v[38:41], v127, s[44:45]
	global_load_dwordx4 v[42:45], v128, s[44:45]
	global_load_dwordx4 v[46:49], v129, s[44:45]
	ds_read_b128 v[110:113], v134
	ds_read_b128 v[114:117], v135
	ds_read_b128 v[118:121], v136
	ds_read_b128 v[122:125], v137
	ds_read2_b32 v[126:127], v191 offset0:160 offset1:164
	ds_read2_b32 v[128:129], v191 offset0:168 offset1:172
	v_pk_mul_f32 v[66:67], v[66:67], s[58:59] op_sel_hi:[1,0]
	v_pk_mul_f32 v[68:69], v[68:69], s[58:59] op_sel_hi:[1,0]
	v_pk_mul_f32 v[70:71], v[70:71], s[58:59] op_sel_hi:[1,0]
	v_pk_mul_f32 v[72:73], v[72:73], s[58:59] op_sel_hi:[1,0]
	s_mov_b64 exec, 0xffff
	ds_write_b128 v199, v[66:69] offset:2112
	ds_write_b128 v199, v[70:73] offset:2128
	s_mov_b64 exec, -1
	s_waitcnt lgkmcnt(4)
	v_mfma_f32_16x16x32_bf16 v[226:229], v[2:5], v[110:113], 0
	v_mfma_f32_16x16x32_bf16 v[230:233], v[10:13], v[118:121], 0
	v_mfma_f32_16x16x32_bf16 v[226:229], v[6:9], v[114:117], v[226:229]
	v_mfma_f32_16x16x32_bf16 v[230:233], v[14:17], v[122:125], v[230:233]
	s_waitcnt vmcnt(12)
	ds_write_b128 v130, v[50:53]
	ds_write_b128 v131, v[54:57]
	ds_write_b128 v132, v[58:61]
	ds_write_b128 v133, v[62:65]
	s_waitcnt lgkmcnt(4)
	v_lshl_add_u32 v126, v126, 8, v194
	v_lshl_add_u32 v127, v127, 8, v194
	v_lshl_add_u32 v128, v128, 8, v194
	v_lshl_add_u32 v129, v129, 8, v194
	global_load_dwordx4 v[50:53], v126, s[44:45]
	global_load_dwordx4 v[54:57], v127, s[44:45]
	global_load_dwordx4 v[58:61], v128, s[44:45]
	global_load_dwordx4 v[62:65], v129, s[44:45]
	ds_read_b128 v[110:113], v134
	ds_read_b128 v[114:117], v135
	ds_read_b128 v[118:121], v136
	ds_read_b128 v[122:125], v137
	ds_read2_b32 v[126:127], v191 offset0:176 offset1:180
	ds_read2_b32 v[128:129], v191 offset0:184 offset1:188
	v_pk_mul_f32 v[226:227], v[226:227], s[58:59] op_sel_hi:[1,0]
	v_pk_mul_f32 v[228:229], v[228:229], s[58:59] op_sel_hi:[1,0]
	v_pk_mul_f32 v[230:231], v[230:231], s[58:59] op_sel_hi:[1,0]
	v_pk_mul_f32 v[232:233], v[232:233], s[58:59] op_sel_hi:[1,0]
	s_mov_b64 exec, 0xffff
	ds_write_b128 v199, v[226:229] offset:2624
	ds_write_b128 v199, v[230:233] offset:2640
	s_mov_b64 exec, -1
	s_waitcnt lgkmcnt(4)
	v_mfma_f32_16x16x32_bf16 v[66:69], v[2:5], v[110:113], 0
	v_mfma_f32_16x16x32_bf16 v[70:73], v[10:13], v[118:121], 0
	v_mfma_f32_16x16x32_bf16 v[66:69], v[6:9], v[114:117], v[66:69]
	v_mfma_f32_16x16x32_bf16 v[70:73], v[14:17], v[122:125], v[70:73]
	s_waitcnt vmcnt(12)
	ds_write_b128 v130, v[94:97]
	ds_write_b128 v131, v[98:101]
	ds_write_b128 v132, v[102:105]
	ds_write_b128 v133, v[106:109]
	s_waitcnt lgkmcnt(4)
	v_lshl_add_u32 v126, v126, 8, v194
	v_lshl_add_u32 v127, v127, 8, v194
	v_lshl_add_u32 v128, v128, 8, v194
	v_lshl_add_u32 v129, v129, 8, v194
	global_load_dwordx4 v[94:97], v126, s[44:45]
	global_load_dwordx4 v[98:101], v127, s[44:45]
	global_load_dwordx4 v[102:105], v128, s[44:45]
	global_load_dwordx4 v[106:109], v129, s[44:45]
	ds_read_b128 v[110:113], v134
	ds_read_b128 v[114:117], v135
	ds_read_b128 v[118:121], v136
	ds_read_b128 v[122:125], v137
	ds_read2_b32 v[126:127], v191 offset0:192 offset1:196
	ds_read2_b32 v[128:129], v191 offset0:200 offset1:204
	v_pk_mul_f32 v[66:67], v[66:67], s[58:59] op_sel_hi:[1,0]
	v_pk_mul_f32 v[68:69], v[68:69], s[58:59] op_sel_hi:[1,0]
	v_pk_mul_f32 v[70:71], v[70:71], s[58:59] op_sel_hi:[1,0]
	v_pk_mul_f32 v[72:73], v[72:73], s[58:59] op_sel_hi:[1,0]
	s_mov_b64 exec, 0xffff
	ds_write_b128 v199, v[66:69] offset:3168
	ds_write_b128 v199, v[70:73] offset:3184
	s_mov_b64 exec, -1
	s_waitcnt lgkmcnt(4)
	v_mfma_f32_16x16x32_bf16 v[226:229], v[2:5], v[110:113], 0
	v_mfma_f32_16x16x32_bf16 v[230:233], v[10:13], v[118:121], 0
	v_mfma_f32_16x16x32_bf16 v[226:229], v[6:9], v[114:117], v[226:229]
	v_mfma_f32_16x16x32_bf16 v[230:233], v[14:17], v[122:125], v[230:233]
	s_waitcnt vmcnt(12)
	ds_write_b128 v130, v[18:21]
	ds_write_b128 v131, v[22:25]
	ds_write_b128 v132, v[26:29]
	ds_write_b128 v133, v[30:33]
	s_waitcnt lgkmcnt(4)
	v_lshl_add_u32 v126, v126, 8, v194
	v_lshl_add_u32 v127, v127, 8, v194
	v_lshl_add_u32 v128, v128, 8, v194
	v_lshl_add_u32 v129, v129, 8, v194
	global_load_dwordx4 v[18:21], v126, s[44:45]
	global_load_dwordx4 v[22:25], v127, s[44:45]
	global_load_dwordx4 v[26:29], v128, s[44:45]
	global_load_dwordx4 v[30:33], v129, s[44:45]
	ds_read_b128 v[110:113], v134
	ds_read_b128 v[114:117], v135
	ds_read_b128 v[118:121], v136
	ds_read_b128 v[122:125], v137
	ds_read2_b32 v[126:127], v191 offset0:208 offset1:212
	ds_read2_b32 v[128:129], v191 offset0:216 offset1:220
	v_pk_mul_f32 v[226:227], v[226:227], s[58:59] op_sel_hi:[1,0]
	v_pk_mul_f32 v[228:229], v[228:229], s[58:59] op_sel_hi:[1,0]
	v_pk_mul_f32 v[230:231], v[230:231], s[58:59] op_sel_hi:[1,0]
	v_pk_mul_f32 v[232:233], v[232:233], s[58:59] op_sel_hi:[1,0]
	s_mov_b64 exec, 0xffff
	ds_write_b128 v199, v[226:229] offset:3680
	ds_write_b128 v199, v[230:233] offset:3696
	s_mov_b64 exec, -1
	s_waitcnt lgkmcnt(4)
	v_mfma_f32_16x16x32_bf16 v[66:69], v[2:5], v[110:113], 0
	v_mfma_f32_16x16x32_bf16 v[70:73], v[10:13], v[118:121], 0
	v_mfma_f32_16x16x32_bf16 v[66:69], v[6:9], v[114:117], v[66:69]
	v_mfma_f32_16x16x32_bf16 v[70:73], v[14:17], v[122:125], v[70:73]
	s_waitcnt vmcnt(12)
	ds_write_b128 v130, v[34:37]
	ds_write_b128 v131, v[38:41]
	ds_write_b128 v132, v[42:45]
	ds_write_b128 v133, v[46:49]
	s_waitcnt lgkmcnt(4)
	v_lshl_add_u32 v126, v126, 8, v194
	v_lshl_add_u32 v127, v127, 8, v194
	v_lshl_add_u32 v128, v128, 8, v194
	v_lshl_add_u32 v129, v129, 8, v194
	global_load_dwordx4 v[34:37], v126, s[44:45]
	global_load_dwordx4 v[38:41], v127, s[44:45]
	global_load_dwordx4 v[42:45], v128, s[44:45]
	global_load_dwordx4 v[46:49], v129, s[44:45]
	ds_read_b128 v[110:113], v134
	ds_read_b128 v[114:117], v135
	ds_read_b128 v[118:121], v136
	ds_read_b128 v[122:125], v137
	ds_read2_b32 v[126:127], v191 offset0:224 offset1:228
	ds_read2_b32 v[128:129], v191 offset0:232 offset1:236
	v_pk_mul_f32 v[66:67], v[66:67], s[58:59] op_sel_hi:[1,0]
	v_pk_mul_f32 v[68:69], v[68:69], s[58:59] op_sel_hi:[1,0]
	v_pk_mul_f32 v[70:71], v[70:71], s[58:59] op_sel_hi:[1,0]
	v_pk_mul_f32 v[72:73], v[72:73], s[58:59] op_sel_hi:[1,0]
	s_mov_b64 exec, 0xffff
	ds_write_b128 v199, v[66:69] offset:4224
	ds_write_b128 v199, v[70:73] offset:4240
	s_mov_b64 exec, -1
	s_waitcnt lgkmcnt(4)
	v_mfma_f32_16x16x32_bf16 v[226:229], v[2:5], v[110:113], 0
	v_mfma_f32_16x16x32_bf16 v[230:233], v[10:13], v[118:121], 0
	v_mfma_f32_16x16x32_bf16 v[226:229], v[6:9], v[114:117], v[226:229]
	v_mfma_f32_16x16x32_bf16 v[230:233], v[14:17], v[122:125], v[230:233]
	s_waitcnt vmcnt(12)
	ds_write_b128 v130, v[50:53]
	ds_write_b128 v131, v[54:57]
	ds_write_b128 v132, v[58:61]
	ds_write_b128 v133, v[62:65]
	s_waitcnt lgkmcnt(4)
	v_lshl_add_u32 v126, v126, 8, v194
	v_lshl_add_u32 v127, v127, 8, v194
	v_lshl_add_u32 v128, v128, 8, v194
	v_lshl_add_u32 v129, v129, 8, v194
	global_load_dwordx4 v[50:53], v126, s[44:45]
	global_load_dwordx4 v[54:57], v127, s[44:45]
	global_load_dwordx4 v[58:61], v128, s[44:45]
	global_load_dwordx4 v[62:65], v129, s[44:45]
	ds_read_b128 v[110:113], v134
	ds_read_b128 v[114:117], v135
	ds_read_b128 v[118:121], v136
	ds_read_b128 v[122:125], v137
	ds_read2_b32 v[126:127], v191 offset0:240 offset1:244
	ds_read2_b32 v[128:129], v191 offset0:248 offset1:252
	v_pk_mul_f32 v[226:227], v[226:227], s[58:59] op_sel_hi:[1,0]
	v_pk_mul_f32 v[228:229], v[228:229], s[58:59] op_sel_hi:[1,0]
	v_pk_mul_f32 v[230:231], v[230:231], s[58:59] op_sel_hi:[1,0]
	v_pk_mul_f32 v[232:233], v[232:233], s[58:59] op_sel_hi:[1,0]
	s_mov_b64 exec, 0xffff
	ds_write_b128 v199, v[226:229] offset:4736
	ds_write_b128 v199, v[230:233] offset:4752
	s_mov_b64 exec, -1
	s_waitcnt lgkmcnt(4)
	v_mfma_f32_16x16x32_bf16 v[66:69], v[2:5], v[110:113], 0
	v_mfma_f32_16x16x32_bf16 v[70:73], v[10:13], v[118:121], 0
	v_mfma_f32_16x16x32_bf16 v[66:69], v[6:9], v[114:117], v[66:69]
	v_mfma_f32_16x16x32_bf16 v[70:73], v[14:17], v[122:125], v[70:73]
	s_waitcnt vmcnt(12)
	ds_write_b128 v130, v[94:97]
	ds_write_b128 v131, v[98:101]
	ds_write_b128 v132, v[102:105]
	ds_write_b128 v133, v[106:109]
	s_waitcnt lgkmcnt(4)
	v_lshl_add_u32 v126, v126, 8, v194
	v_lshl_add_u32 v127, v127, 8, v194
	v_lshl_add_u32 v128, v128, 8, v194
	v_lshl_add_u32 v129, v129, 8, v194
	global_load_dwordx4 v[94:97], v126, s[44:45]
	global_load_dwordx4 v[98:101], v127, s[44:45]
	global_load_dwordx4 v[102:105], v128, s[44:45]
	global_load_dwordx4 v[106:109], v129, s[44:45]
	ds_read_b128 v[110:113], v134
	ds_read_b128 v[114:117], v135
	ds_read_b128 v[118:121], v136
	ds_read_b128 v[122:125], v137
	v_pk_mul_f32 v[66:67], v[66:67], s[58:59] op_sel_hi:[1,0]
	v_pk_mul_f32 v[68:69], v[68:69], s[58:59] op_sel_hi:[1,0]
	v_pk_mul_f32 v[70:71], v[70:71], s[58:59] op_sel_hi:[1,0]
	v_pk_mul_f32 v[72:73], v[72:73], s[58:59] op_sel_hi:[1,0]
	s_mov_b64 exec, 0xffff
	ds_write_b128 v199, v[66:69] offset:5280
	ds_write_b128 v199, v[70:73] offset:5296
	s_mov_b64 exec, -1
	s_waitcnt lgkmcnt(2)
	v_mfma_f32_16x16x32_bf16 v[226:229], v[2:5], v[110:113], 0
	v_mfma_f32_16x16x32_bf16 v[230:233], v[10:13], v[118:121], 0
	v_mfma_f32_16x16x32_bf16 v[226:229], v[6:9], v[114:117], v[226:229]
	v_mfma_f32_16x16x32_bf16 v[230:233], v[14:17], v[122:125], v[230:233]
	s_waitcnt vmcnt(12)
	ds_write_b128 v130, v[18:21]
	ds_write_b128 v131, v[22:25]
	ds_write_b128 v132, v[26:29]
	ds_write_b128 v133, v[30:33]
	ds_read_b128 v[110:113], v134
	ds_read_b128 v[114:117], v135
	ds_read_b128 v[118:121], v136
	ds_read_b128 v[122:125], v137
	v_pk_mul_f32 v[226:227], v[226:227], s[58:59] op_sel_hi:[1,0]
	v_pk_mul_f32 v[228:229], v[228:229], s[58:59] op_sel_hi:[1,0]
	v_pk_mul_f32 v[230:231], v[230:231], s[58:59] op_sel_hi:[1,0]
	v_pk_mul_f32 v[232:233], v[232:233], s[58:59] op_sel_hi:[1,0]
	s_mov_b64 exec, 0xffff
	ds_write_b128 v199, v[226:229] offset:5792
	ds_write_b128 v199, v[230:233] offset:5808
	s_mov_b64 exec, -1
	s_waitcnt lgkmcnt(2)
	v_mfma_f32_16x16x32_bf16 v[66:69], v[2:5], v[110:113], 0
	v_mfma_f32_16x16x32_bf16 v[70:73], v[10:13], v[118:121], 0
	v_mfma_f32_16x16x32_bf16 v[66:69], v[6:9], v[114:117], v[66:69]
	v_mfma_f32_16x16x32_bf16 v[70:73], v[14:17], v[122:125], v[70:73]
	s_waitcnt vmcnt(8)
	ds_write_b128 v130, v[34:37]
	ds_write_b128 v131, v[38:41]
	ds_write_b128 v132, v[42:45]
	ds_write_b128 v133, v[46:49]
	ds_read_b128 v[110:113], v134
	ds_read_b128 v[114:117], v135
	ds_read_b128 v[118:121], v136
	ds_read_b128 v[122:125], v137
	v_pk_mul_f32 v[66:67], v[66:67], s[58:59] op_sel_hi:[1,0]
	v_pk_mul_f32 v[68:69], v[68:69], s[58:59] op_sel_hi:[1,0]
	v_pk_mul_f32 v[70:71], v[70:71], s[58:59] op_sel_hi:[1,0]
	v_pk_mul_f32 v[72:73], v[72:73], s[58:59] op_sel_hi:[1,0]
	s_mov_b64 exec, 0xffff
	ds_write_b128 v199, v[66:69] offset:6336
	ds_write_b128 v199, v[70:73] offset:6352
	s_mov_b64 exec, -1
	s_waitcnt lgkmcnt(2)
	v_mfma_f32_16x16x32_bf16 v[226:229], v[2:5], v[110:113], 0
	v_mfma_f32_16x16x32_bf16 v[230:233], v[10:13], v[118:121], 0
	v_mfma_f32_16x16x32_bf16 v[226:229], v[6:9], v[114:117], v[226:229]
	v_mfma_f32_16x16x32_bf16 v[230:233], v[14:17], v[122:125], v[230:233]
	s_waitcnt vmcnt(4)
	ds_write_b128 v130, v[50:53]
	ds_write_b128 v131, v[54:57]
	ds_write_b128 v132, v[58:61]
	ds_write_b128 v133, v[62:65]
	ds_read_b128 v[110:113], v134
	ds_read_b128 v[114:117], v135
	ds_read_b128 v[118:121], v136
	ds_read_b128 v[122:125], v137
	v_pk_mul_f32 v[226:227], v[226:227], s[58:59] op_sel_hi:[1,0]
	v_pk_mul_f32 v[228:229], v[228:229], s[58:59] op_sel_hi:[1,0]
	v_pk_mul_f32 v[230:231], v[230:231], s[58:59] op_sel_hi:[1,0]
	v_pk_mul_f32 v[232:233], v[232:233], s[58:59] op_sel_hi:[1,0]
	s_mov_b64 exec, 0xffff
	ds_write_b128 v199, v[226:229] offset:6848
	ds_write_b128 v199, v[230:233] offset:6864
	s_mov_b64 exec, -1
	s_waitcnt lgkmcnt(2)
	v_mfma_f32_16x16x32_bf16 v[66:69], v[2:5], v[110:113], 0
	v_mfma_f32_16x16x32_bf16 v[70:73], v[10:13], v[118:121], 0
	v_mfma_f32_16x16x32_bf16 v[66:69], v[6:9], v[114:117], v[66:69]
	v_mfma_f32_16x16x32_bf16 v[70:73], v[14:17], v[122:125], v[70:73]
	s_waitcnt vmcnt(0)
	ds_write_b128 v130, v[94:97]
	ds_write_b128 v131, v[98:101]
	ds_write_b128 v132, v[102:105]
	ds_write_b128 v133, v[106:109]
	ds_read_b128 v[110:113], v134
	ds_read_b128 v[114:117], v135
	ds_read_b128 v[118:121], v136
	ds_read_b128 v[122:125], v137
	v_pk_mul_f32 v[66:67], v[66:67], s[58:59] op_sel_hi:[1,0]
	v_pk_mul_f32 v[68:69], v[68:69], s[58:59] op_sel_hi:[1,0]
	v_pk_mul_f32 v[70:71], v[70:71], s[58:59] op_sel_hi:[1,0]
	v_pk_mul_f32 v[72:73], v[72:73], s[58:59] op_sel_hi:[1,0]
	s_mov_b64 exec, 0xffff
	ds_write_b128 v199, v[66:69] offset:7392
	ds_write_b128 v199, v[70:73] offset:7408
	s_mov_b64 exec, -1
	s_waitcnt lgkmcnt(2)
	v_mfma_f32_16x16x32_bf16 v[226:229], v[2:5], v[110:113], 0
	v_mfma_f32_16x16x32_bf16 v[230:233], v[10:13], v[118:121], 0
	v_mfma_f32_16x16x32_bf16 v[226:229], v[6:9], v[114:117], v[226:229]
	v_mfma_f32_16x16x32_bf16 v[230:233], v[14:17], v[122:125], v[230:233]
	s_nop 7
	s_nop 1
	v_pk_mul_f32 v[226:227], v[226:227], s[58:59] op_sel_hi:[1,0]
	v_pk_mul_f32 v[228:229], v[228:229], s[58:59] op_sel_hi:[1,0]
	v_pk_mul_f32 v[230:231], v[230:231], s[58:59] op_sel_hi:[1,0]
	v_pk_mul_f32 v[232:233], v[232:233], s[58:59] op_sel_hi:[1,0]
	s_mov_b64 exec, 0xffff
	ds_write_b128 v199, v[226:229] offset:7904
	ds_write_b128 v199, v[230:233] offset:7920
	s_mov_b64 exec, -1
	v_lshl_add_u32 v191, v223, 2, s56
	v_lshlrev_b32_e32 v194, 4, v202
	ds_read2_b32 v[126:127], v191 offset0:0 offset1:4
	ds_read2_b32 v[128:129], v191 offset0:8 offset1:12
	ds_read2_b32 v[130:131], v191 offset0:16 offset1:20
	ds_read2_b32 v[132:133], v191 offset0:24 offset1:28
	s_waitcnt lgkmcnt(0)
	v_lshl_add_u32 v126, v126, 8, v194
	v_lshl_add_u32 v127, v127, 8, v194
	v_lshl_add_u32 v128, v128, 8, v194
	v_lshl_add_u32 v129, v129, 8, v194
	v_lshl_add_u32 v130, v130, 8, v194
	v_lshl_add_u32 v131, v131, 8, v194
	v_lshl_add_u32 v132, v132, 8, v194
	v_lshl_add_u32 v133, v133, 8, v194
	global_load_dwordx4 v[18:21], v126, s[46:47]
	global_load_dwordx4 v[22:25], v127, s[46:47]
	global_load_dwordx4 v[26:29], v128, s[46:47]
	global_load_dwordx4 v[30:33], v129, s[46:47]
	global_load_dwordx4 v[34:37], v130, s[46:47]
	global_load_dwordx4 v[38:41], v131, s[46:47]
	global_load_dwordx4 v[42:45], v132, s[46:47]
	global_load_dwordx4 v[46:49], v133, s[46:47]
	ds_read2_b32 v[126:127], v191 offset0:32 offset1:36
	ds_read2_b32 v[128:129], v191 offset0:40 offset1:44
	ds_read2_b32 v[130:131], v191 offset0:48 offset1:52
	ds_read2_b32 v[132:133], v191 offset0:56 offset1:60
	s_waitcnt lgkmcnt(0)
	v_lshl_add_u32 v126, v126, 8, v194
	v_lshl_add_u32 v127, v127, 8, v194
	v_lshl_add_u32 v128, v128, 8, v194
	v_lshl_add_u32 v129, v129, 8, v194
	v_lshl_add_u32 v130, v130, 8, v194
	v_lshl_add_u32 v131, v131, 8, v194
	v_lshl_add_u32 v132, v132, 8, v194
	v_lshl_add_u32 v133, v133, 8, v194
	global_load_dwordx4 v[94:97], v126, s[46:47]
	global_load_dwordx4 v[98:101], v127, s[46:47]
	global_load_dwordx4 v[102:105], v128, s[46:47]
	global_load_dwordx4 v[106:109], v129, s[46:47]
	global_load_dwordx4 v[110:113], v130, s[46:47]
	global_load_dwordx4 v[114:117], v131, s[46:47]
	global_load_dwordx4 v[118:121], v132, s[46:47]
	global_load_dwordx4 v[122:125], v133, s[46:47]
	v_and_b32_e32 v142, 7, v219
	v_lshrrev_b32_e32 v143, 3, v219
	v_mul_u32_u24_e32 v144, 0x420, v143
	v_lshl_add_u32 v144, v142, 2, v144
	v_add_u32_e32 v144, s55, v144
	ds_read2_b32 v[50:51], v144 offset0:0 offset1:8
	ds_read2_b32 v[52:53], v144 offset0:16 offset1:24
	ds_read2_b32 v[54:55], v144 offset0:32 offset1:40
	ds_read2_b32 v[56:57], v144 offset0:48 offset1:56
	ds_read2_b32 v[58:59], v144 offset0:64 offset1:72
	ds_read2_b32 v[60:61], v144 offset0:80 offset1:88
	ds_read2_b32 v[62:63], v144 offset0:96 offset1:104
	ds_read2_b32 v[64:65], v144 offset0:112 offset1:120
	ds_read2_b32 v[2:3], v144 offset0:128 offset1:136
	ds_read2_b32 v[4:5], v144 offset0:144 offset1:152
	ds_read2_b32 v[6:7], v144 offset0:160 offset1:168
	ds_read2_b32 v[8:9], v144 offset0:176 offset1:184
	ds_read2_b32 v[10:11], v144 offset0:192 offset1:200
	ds_read2_b32 v[12:13], v144 offset0:208 offset1:216
	ds_read2_b32 v[14:15], v144 offset0:224 offset1:232
	ds_read2_b32 v[16:17], v144 offset0:240 offset1:248
	s_waitcnt lgkmcnt(0)
	v_max3_f32 v145, v50, v51, v52
	v_max3_f32 v145, v145, v53, v54
	v_max3_f32 v145, v145, v55, v56
	v_max3_f32 v145, v145, v57, v58
	v_max3_f32 v145, v145, v59, v60
	v_max3_f32 v145, v145, v61, v62
	v_max3_f32 v145, v145, v63, v64
	v_max3_f32 v145, v145, v65, v2
	v_max3_f32 v145, v145, v3, v4
	v_max3_f32 v145, v145, v5, v6
	v_max3_f32 v145, v145, v7, v8
	v_max3_f32 v145, v145, v9, v10
	v_max3_f32 v145, v145, v11, v12
	v_max3_f32 v145, v145, v13, v14
	v_max3_f32 v145, v145, v15, v16
	v_max_f32_e32 v145, v145, v17
	s_nop 1
	v_mov_b32_dpp v0, v145 row_ror:8 row_mask:0xf bank_mask:0xf
	s_nop 1
	v_max_f32_e32 v145, v145, v0
	v_mov_b32_e32 v0, v145
	s_nop 1
	v_permlane16_swap_b32_e32 v145, v0
	s_nop 1
	v_max_f32_e32 v145, v145, v0
	v_mov_b32_e32 v0, v145
	s_nop 1
	v_permlane32_swap_b32_e32 v145, v0
	s_nop 1
	v_max_f32_e32 v145, v145, v0
	v_sub_f32_e32 v50, v50, v145
	v_sub_f32_e32 v51, v51, v145
	v_sub_f32_e32 v52, v52, v145
	v_sub_f32_e32 v53, v53, v145
	v_sub_f32_e32 v54, v54, v145
	v_sub_f32_e32 v55, v55, v145
	v_sub_f32_e32 v56, v56, v145
	v_sub_f32_e32 v57, v57, v145
	v_sub_f32_e32 v58, v58, v145
	v_sub_f32_e32 v59, v59, v145
	v_sub_f32_e32 v60, v60, v145
	v_sub_f32_e32 v61, v61, v145
	v_sub_f32_e32 v62, v62, v145
	v_sub_f32_e32 v63, v63, v145
	v_sub_f32_e32 v64, v64, v145
	v_sub_f32_e32 v65, v65, v145
	v_sub_f32_e32 v2, v2, v145
	v_sub_f32_e32 v3, v3, v145
	v_sub_f32_e32 v4, v4, v145
	v_sub_f32_e32 v5, v5, v145
	v_sub_f32_e32 v6, v6, v145
	v_sub_f32_e32 v7, v7, v145
	v_sub_f32_e32 v8, v8, v145
	v_sub_f32_e32 v9, v9, v145
	v_sub_f32_e32 v10, v10, v145
	v_sub_f32_e32 v11, v11, v145
	v_sub_f32_e32 v12, v12, v145
	v_sub_f32_e32 v13, v13, v145
	v_sub_f32_e32 v14, v14, v145
	v_sub_f32_e32 v15, v15, v145
	v_sub_f32_e32 v16, v16, v145
	v_sub_f32_e32 v17, v17, v145
	v_mul_f32_e32 v50, 0x3fb8aa3b, v50
	v_mul_f32_e32 v51, 0x3fb8aa3b, v51
	v_mul_f32_e32 v52, 0x3fb8aa3b, v52
	v_mul_f32_e32 v53, 0x3fb8aa3b, v53
	v_mul_f32_e32 v54, 0x3fb8aa3b, v54
	v_mul_f32_e32 v55, 0x3fb8aa3b, v55
	v_mul_f32_e32 v56, 0x3fb8aa3b, v56
	v_mul_f32_e32 v57, 0x3fb8aa3b, v57
	v_mul_f32_e32 v58, 0x3fb8aa3b, v58
	v_mul_f32_e32 v59, 0x3fb8aa3b, v59
	v_mul_f32_e32 v60, 0x3fb8aa3b, v60
	v_mul_f32_e32 v61, 0x3fb8aa3b, v61
	v_mul_f32_e32 v62, 0x3fb8aa3b, v62
	v_mul_f32_e32 v63, 0x3fb8aa3b, v63
	v_mul_f32_e32 v64, 0x3fb8aa3b, v64
	v_mul_f32_e32 v65, 0x3fb8aa3b, v65
	v_mul_f32_e32 v2, 0x3fb8aa3b, v2
	v_mul_f32_e32 v3, 0x3fb8aa3b, v3
	v_mul_f32_e32 v4, 0x3fb8aa3b, v4
	v_mul_f32_e32 v5, 0x3fb8aa3b, v5
	v_mul_f32_e32 v6, 0x3fb8aa3b, v6
	v_mul_f32_e32 v7, 0x3fb8aa3b, v7
	v_mul_f32_e32 v8, 0x3fb8aa3b, v8
	v_mul_f32_e32 v9, 0x3fb8aa3b, v9
	v_mul_f32_e32 v10, 0x3fb8aa3b, v10
	v_mul_f32_e32 v11, 0x3fb8aa3b, v11
	v_mul_f32_e32 v12, 0x3fb8aa3b, v12
	v_mul_f32_e32 v13, 0x3fb8aa3b, v13
	v_mul_f32_e32 v14, 0x3fb8aa3b, v14
	v_mul_f32_e32 v15, 0x3fb8aa3b, v15
	v_mul_f32_e32 v16, 0x3fb8aa3b, v16
	v_mul_f32_e32 v17, 0x3fb8aa3b, v17
	v_exp_f32_e32 v50, v50
	v_exp_f32_e32 v51, v51
	v_exp_f32_e32 v52, v52
	v_exp_f32_e32 v53, v53
	v_exp_f32_e32 v54, v54
	v_exp_f32_e32 v55, v55
	v_exp_f32_e32 v56, v56
	v_exp_f32_e32 v57, v57
	v_exp_f32_e32 v58, v58
	v_exp_f32_e32 v59, v59
	v_exp_f32_e32 v60, v60
	v_exp_f32_e32 v61, v61
	v_exp_f32_e32 v62, v62
	v_exp_f32_e32 v63, v63
	v_exp_f32_e32 v64, v64
	v_exp_f32_e32 v65, v65
	v_exp_f32_e32 v2, v2
	v_exp_f32_e32 v3, v3
	v_exp_f32_e32 v4, v4
	v_exp_f32_e32 v5, v5
	v_exp_f32_e32 v6, v6
	v_exp_f32_e32 v7, v7
	v_exp_f32_e32 v8, v8
	v_exp_f32_e32 v9, v9
	v_exp_f32_e32 v10, v10
	v_exp_f32_e32 v11, v11
	v_exp_f32_e32 v12, v12
	v_exp_f32_e32 v13, v13
	v_exp_f32_e32 v14, v14
	v_exp_f32_e32 v15, v15
	v_exp_f32_e32 v16, v16
	v_exp_f32_e32 v17, v17
	s_nop 0
	v_add_f32_e32 v145, v50, v51
	v_add_f32_e32 v145, v145, v52
	v_add_f32_e32 v145, v145, v53
	v_add_f32_e32 v145, v145, v54
	v_add_f32_e32 v145, v145, v55
	v_add_f32_e32 v145, v145, v56
	v_add_f32_e32 v145, v145, v57
	v_add_f32_e32 v145, v145, v58
	v_add_f32_e32 v145, v145, v59
	v_add_f32_e32 v145, v145, v60
	v_add_f32_e32 v145, v145, v61
	v_add_f32_e32 v145, v145, v62
	v_add_f32_e32 v145, v145, v63
	v_add_f32_e32 v145, v145, v64
	v_add_f32_e32 v145, v145, v65
	v_add_f32_e32 v145, v145, v2
	v_add_f32_e32 v145, v145, v3
	v_add_f32_e32 v145, v145, v4
	v_add_f32_e32 v145, v145, v5
	v_add_f32_e32 v145, v145, v6
	v_add_f32_e32 v145, v145, v7
	v_add_f32_e32 v145, v145, v8
	v_add_f32_e32 v145, v145, v9
	v_add_f32_e32 v145, v145, v10
	v_add_f32_e32 v145, v145, v11
	v_add_f32_e32 v145, v145, v12
	v_add_f32_e32 v145, v145, v13
	v_add_f32_e32 v145, v145, v14
	v_add_f32_e32 v145, v145, v15
	v_add_f32_e32 v145, v145, v16
	v_add_f32_e32 v145, v145, v17
	v_cvt_pk_bf16_f32 v66, v50, v51
	v_cvt_pk_bf16_f32 v67, v52, v53
	v_cvt_pk_bf16_f32 v68, v54, v55
	v_cvt_pk_bf16_f32 v69, v56, v57
	v_cvt_pk_bf16_f32 v70, v58, v59
	v_cvt_pk_bf16_f32 v71, v60, v61
	v_cvt_pk_bf16_f32 v72, v62, v63
	v_cvt_pk_bf16_f32 v73, v64, v65
	v_cvt_pk_bf16_f32 v226, v2, v3
	v_cvt_pk_bf16_f32 v227, v4, v5
	v_cvt_pk_bf16_f32 v228, v6, v7
	v_cvt_pk_bf16_f32 v229, v8, v9
	v_cvt_pk_bf16_f32 v230, v10, v11
	v_cvt_pk_bf16_f32 v231, v12, v13
	v_cvt_pk_bf16_f32 v232, v14, v15
	v_cvt_pk_bf16_f32 v233, v16, v17
	v_mul_u32_u24_e32 v144, 0x210, v142
	v_lshl_add_u32 v144, v143, 6, v144
	v_add_u32_e32 v144, s55, v144
	ds_write_b128 v144, v[66:69] offset:9216
	ds_write_b128 v144, v[70:73] offset:9232
	ds_write_b128 v144, v[226:229] offset:9248
	ds_write_b128 v144, v[230:233] offset:9264
	s_nop 1
	v_mov_b32_dpp v0, v145 row_ror:8 row_mask:0xf bank_mask:0xf
	s_nop 1
	v_add_f32_e32 v145, v145, v0
	v_mov_b32_e32 v0, v145
	s_nop 1
	v_permlane16_swap_b32_e32 v145, v0
	s_nop 1
	v_add_f32_e32 v145, v145, v0
	v_mov_b32_e32 v0, v145
	s_nop 1
	v_permlane32_swap_b32_e32 v145, v0
	s_nop 1
	v_add_f32_e32 v145, v145, v0
	v_rcp_f32_e32 v145, v145
	s_nop 1
	v_readlane_b32 s62, v145, 0
	v_readlane_b32 s63, v145, 1
	v_readlane_b32 s64, v145, 2
	v_readlane_b32 s65, v145, 3
	v_readlane_b32 s66, v145, 4
	v_readlane_b32 s67, v145, 5
	v_readlane_b32 s68, v145, 6
	v_readlane_b32 s69, v145, 7
	v_mov_b32_e32 v50, 0
	v_mov_b32_e32 v51, 0
	v_mov_b32_e32 v52, 0
	v_mov_b32_e32 v53, 0
	v_mov_b32_e32 v54, 0
	v_mov_b32_e32 v55, 0
	v_mov_b32_e32 v56, 0
	v_mov_b32_e32 v57, 0
	v_mov_b32_e32 v58, 0
	v_mov_b32_e32 v59, 0
	v_mov_b32_e32 v60, 0
	v_mov_b32_e32 v61, 0
	v_mov_b32_e32 v62, 0
	v_mov_b32_e32 v63, 0
	v_mov_b32_e32 v64, 0
	v_mov_b32_e32 v65, 0
	v_mov_b32_e32 v66, 0
	v_mov_b32_e32 v67, 0
	v_mov_b32_e32 v68, 0
	v_mov_b32_e32 v69, 0
	v_mov_b32_e32 v70, 0
	v_mov_b32_e32 v71, 0
	v_mov_b32_e32 v72, 0
	v_mov_b32_e32 v73, 0
	v_mov_b32_e32 v74, 0
	v_mov_b32_e32 v75, 0
	v_mov_b32_e32 v76, 0
	v_mov_b32_e32 v77, 0
	v_mov_b32_e32 v226, 0
	v_mov_b32_e32 v227, 0
	v_mov_b32_e32 v228, 0
	v_mov_b32_e32 v229, 0
	v_mov_b32_e32 v2, 0
	v_mov_b32_e32 v3, 0
	v_mov_b32_e32 v4, 0
	v_mov_b32_e32 v5, 0
	v_mov_b32_e32 v6, 0
	v_mov_b32_e32 v7, 0
	v_mov_b32_e32 v8, 0
	v_mov_b32_e32 v9, 0
	v_mul_u32_u24_e32 v199, 0x120, v223
	v_add3_u32 v199, v199, v194, s55
	v_mul_u32_u24_e32 v142, 0x210, v202
	v_lshl_add_u32 v142, v223, 4, v142
	v_add_u32_e32 v142, s55, v142
	v_lshrrev_b32_e32 v143, 2, v202
	v_lshl_add_u32 v143, v223, 3, v143
	v_mul_u32_u24_e32 v143, 0x120, v143
	v_and_b32_e32 v144, 3, v219
	v_lshl_add_u32 v143, v144, 3, v143
	v_add_u32_e32 v143, s55, v143
	ds_read2_b32 v[126:127], v191 offset0:64 offset1:68
	ds_read2_b32 v[128:129], v191 offset0:72 offset1:76
	ds_read2_b32 v[130:131], v191 offset0:80 offset1:84
	ds_read2_b32 v[132:133], v191 offset0:88 offset1:92
	s_waitcnt vmcnt(8)
	ds_write_b128 v199, v[18:21] offset:0
	ds_write_b128 v199, v[22:25] offset:1152
	ds_write_b128 v199, v[26:29] offset:2304
	ds_write_b128 v199, v[30:33] offset:3456
	ds_write_b128 v199, v[34:37] offset:4608
	ds_write_b128 v199, v[38:41] offset:5760
	ds_write_b128 v199, v[42:45] offset:6912
	ds_write_b128 v199, v[46:49] offset:8064
	s_waitcnt lgkmcnt(8)
	v_lshl_add_u32 v126, v126, 8, v194
	v_lshl_add_u32 v127, v127, 8, v194
	v_lshl_add_u32 v128, v128, 8, v194
	v_lshl_add_u32 v129, v129, 8, v194
	v_lshl_add_u32 v130, v130, 8, v194
	v_lshl_add_u32 v131, v131, 8, v194
	v_lshl_add_u32 v132, v132, 8, v194
	v_lshl_add_u32 v133, v133, 8, v194
	global_load_dwordx4 v[18:21], v126, s[46:47]
	global_load_dwordx4 v[22:25], v127, s[46:47]
	global_load_dwordx4 v[26:29], v128, s[46:47]
	global_load_dwordx4 v[30:33], v129, s[46:47]
	global_load_dwordx4 v[34:37], v130, s[46:47]
	global_load_dwordx4 v[38:41], v131, s[46:47]
	global_load_dwordx4 v[42:45], v132, s[46:47]
	global_load_dwordx4 v[46:49], v133, s[46:47]
	s_mov_b64 exec, s[70:71]
	ds_read_b128 v[2:5], v142 offset:9216
	s_mov_b64 exec, -1
	ds_read_b64_tr_b16 v[10:11], v143 offset:0
	ds_read_b64_tr_b16 v[12:13], v143 offset:1152
	ds_read_b64_tr_b16 v[14:15], v143 offset:32
	ds_read_b64_tr_b16 v[16:17], v143 offset:1184
	ds_read_b64_tr_b16 v[134:135], v143 offset:64
	ds_read_b64_tr_b16 v[136:137], v143 offset:1216
	ds_read_b64_tr_b16 v[138:139], v143 offset:96
	ds_read_b64_tr_b16 v[140:141], v143 offset:1248
	s_waitcnt lgkmcnt(6)
	v_mfma_f32_16x16x32_bf16 v[50:53], v[2:5], v[10:13], v[50:53]
	s_waitcnt lgkmcnt(4)
	v_mfma_f32_16x16x32_bf16 v[54:57], v[2:5], v[14:17], v[54:57]
	s_waitcnt lgkmcnt(2)
	v_mfma_f32_16x16x32_bf16 v[58:61], v[2:5], v[134:137], v[58:61]
	s_waitcnt lgkmcnt(0)
	v_mfma_f32_16x16x32_bf16 v[62:65], v[2:5], v[138:141], v[62:65]
	s_mov_b64 exec, s[70:71]
	ds_read_b128 v[6:9], v142 offset:11328
	s_mov_b64 exec, -1
	ds_read_b64_tr_b16 v[10:11], v143 offset:128
	ds_read_b64_tr_b16 v[12:13], v143 offset:1280
	ds_read_b64_tr_b16 v[14:15], v143 offset:160
	ds_read_b64_tr_b16 v[16:17], v143 offset:1312
	ds_read_b64_tr_b16 v[134:135], v143 offset:192
	ds_read_b64_tr_b16 v[136:137], v143 offset:1344
	ds_read_b64_tr_b16 v[138:139], v143 offset:224
	ds_read_b64_tr_b16 v[140:141], v143 offset:1376
	s_waitcnt lgkmcnt(6)
	v_mfma_f32_16x16x32_bf16 v[66:69], v[6:9], v[10:13], v[66:69]
	s_waitcnt lgkmcnt(4)
	v_mfma_f32_16x16x32_bf16 v[70:73], v[6:9], v[14:17], v[70:73]
	s_waitcnt lgkmcnt(2)
	v_mfma_f32_16x16x32_bf16 v[74:77], v[6:9], v[134:137], v[74:77]
	s_waitcnt lgkmcnt(0)
	v_mfma_f32_16x16x32_bf16 v[226:229], v[6:9], v[138:141], v[226:229]
	ds_read2_b32 v[126:127], v191 offset0:96 offset1:100
	ds_read2_b32 v[128:129], v191 offset0:104 offset1:108
	ds_read2_b32 v[130:131], v191 offset0:112 offset1:116
	ds_read2_b32 v[132:133], v191 offset0:120 offset1:124
	s_waitcnt vmcnt(8)
	ds_write_b128 v199, v[94:97] offset:0
	ds_write_b128 v199, v[98:101] offset:1152
	ds_write_b128 v199, v[102:105] offset:2304
	ds_write_b128 v199, v[106:109] offset:3456
	ds_write_b128 v199, v[110:113] offset:4608
	ds_write_b128 v199, v[114:117] offset:5760
	ds_write_b128 v199, v[118:121] offset:6912
	ds_write_b128 v199, v[122:125] offset:8064
	s_waitcnt lgkmcnt(8)
	v_lshl_add_u32 v126, v126, 8, v194
	v_lshl_add_u32 v127, v127, 8, v194
	v_lshl_add_u32 v128, v128, 8, v194
	v_lshl_add_u32 v129, v129, 8, v194
	v_lshl_add_u32 v130, v130, 8, v194
	v_lshl_add_u32 v131, v131, 8, v194
	v_lshl_add_u32 v132, v132, 8, v194
	v_lshl_add_u32 v133, v133, 8, v194
	global_load_dwordx4 v[94:97], v126, s[46:47]
	global_load_dwordx4 v[98:101], v127, s[46:47]
	global_load_dwordx4 v[102:105], v128, s[46:47]
	global_load_dwordx4 v[106:109], v129, s[46:47]
	global_load_dwordx4 v[110:113], v130, s[46:47]
	global_load_dwordx4 v[114:117], v131, s[46:47]
	global_load_dwordx4 v[118:121], v132, s[46:47]
	global_load_dwordx4 v[122:125], v133, s[46:47]
	s_mov_b64 exec, s[70:71]
	ds_read_b128 v[2:5], v142 offset:9280
	s_mov_b64 exec, -1
	ds_read_b64_tr_b16 v[10:11], v143 offset:0
	ds_read_b64_tr_b16 v[12:13], v143 offset:1152
	ds_read_b64_tr_b16 v[14:15], v143 offset:32
	ds_read_b64_tr_b16 v[16:17], v143 offset:1184
	ds_read_b64_tr_b16 v[134:135], v143 offset:64
	ds_read_b64_tr_b16 v[136:137], v143 offset:1216
	ds_read_b64_tr_b16 v[138:139], v143 offset:96
	ds_read_b64_tr_b16 v[140:141], v143 offset:1248
	s_waitcnt lgkmcnt(6)
	v_mfma_f32_16x16x32_bf16 v[50:53], v[2:5], v[10:13], v[50:53]
	s_waitcnt lgkmcnt(4)
	v_mfma_f32_16x16x32_bf16 v[54:57], v[2:5], v[14:17], v[54:57]
	s_waitcnt lgkmcnt(2)
	v_mfma_f32_16x16x32_bf16 v[58:61], v[2:5], v[134:137], v[58:61]
	s_waitcnt lgkmcnt(0)
	v_mfma_f32_16x16x32_bf16 v[62:65], v[2:5], v[138:141], v[62:65]
	s_mov_b64 exec, s[70:71]
	ds_read_b128 v[6:9], v142 offset:11392
	s_mov_b64 exec, -1
	ds_read_b64_tr_b16 v[10:11], v143 offset:128
	ds_read_b64_tr_b16 v[12:13], v143 offset:1280
	ds_read_b64_tr_b16 v[14:15], v143 offset:160
	ds_read_b64_tr_b16 v[16:17], v143 offset:1312
	ds_read_b64_tr_b16 v[134:135], v143 offset:192
	ds_read_b64_tr_b16 v[136:137], v143 offset:1344
	ds_read_b64_tr_b16 v[138:139], v143 offset:224
	ds_read_b64_tr_b16 v[140:141], v143 offset:1376
	s_waitcnt lgkmcnt(6)
	v_mfma_f32_16x16x32_bf16 v[66:69], v[6:9], v[10:13], v[66:69]
	s_waitcnt lgkmcnt(4)
	v_mfma_f32_16x16x32_bf16 v[70:73], v[6:9], v[14:17], v[70:73]
	s_waitcnt lgkmcnt(2)
	v_mfma_f32_16x16x32_bf16 v[74:77], v[6:9], v[134:137], v[74:77]
	s_waitcnt lgkmcnt(0)
	v_mfma_f32_16x16x32_bf16 v[226:229], v[6:9], v[138:141], v[226:229]
	ds_read2_b32 v[126:127], v191 offset0:128 offset1:132
	ds_read2_b32 v[128:129], v191 offset0:136 offset1:140
	ds_read2_b32 v[130:131], v191 offset0:144 offset1:148
	ds_read2_b32 v[132:133], v191 offset0:152 offset1:156
	s_waitcnt vmcnt(8)
	ds_write_b128 v199, v[18:21] offset:0
	ds_write_b128 v199, v[22:25] offset:1152
	ds_write_b128 v199, v[26:29] offset:2304
	ds_write_b128 v199, v[30:33] offset:3456
	ds_write_b128 v199, v[34:37] offset:4608
	ds_write_b128 v199, v[38:41] offset:5760
	ds_write_b128 v199, v[42:45] offset:6912
	ds_write_b128 v199, v[46:49] offset:8064
	s_waitcnt lgkmcnt(8)
	v_lshl_add_u32 v126, v126, 8, v194
	v_lshl_add_u32 v127, v127, 8, v194
	v_lshl_add_u32 v128, v128, 8, v194
	v_lshl_add_u32 v129, v129, 8, v194
	v_lshl_add_u32 v130, v130, 8, v194
	v_lshl_add_u32 v131, v131, 8, v194
	v_lshl_add_u32 v132, v132, 8, v194
	v_lshl_add_u32 v133, v133, 8, v194
	global_load_dwordx4 v[18:21], v126, s[46:47]
	global_load_dwordx4 v[22:25], v127, s[46:47]
	global_load_dwordx4 v[26:29], v128, s[46:47]
	global_load_dwordx4 v[30:33], v129, s[46:47]
	global_load_dwordx4 v[34:37], v130, s[46:47]
	global_load_dwordx4 v[38:41], v131, s[46:47]
	global_load_dwordx4 v[42:45], v132, s[46:47]
	global_load_dwordx4 v[46:49], v133, s[46:47]
	s_mov_b64 exec, s[70:71]
	ds_read_b128 v[2:5], v142 offset:9344
	s_mov_b64 exec, -1
	ds_read_b64_tr_b16 v[10:11], v143 offset:0
	ds_read_b64_tr_b16 v[12:13], v143 offset:1152
	ds_read_b64_tr_b16 v[14:15], v143 offset:32
	ds_read_b64_tr_b16 v[16:17], v143 offset:1184
	ds_read_b64_tr_b16 v[134:135], v143 offset:64
	ds_read_b64_tr_b16 v[136:137], v143 offset:1216
	ds_read_b64_tr_b16 v[138:139], v143 offset:96
	ds_read_b64_tr_b16 v[140:141], v143 offset:1248
	s_waitcnt lgkmcnt(6)
	v_mfma_f32_16x16x32_bf16 v[50:53], v[2:5], v[10:13], v[50:53]
	s_waitcnt lgkmcnt(4)
	v_mfma_f32_16x16x32_bf16 v[54:57], v[2:5], v[14:17], v[54:57]
	s_waitcnt lgkmcnt(2)
	v_mfma_f32_16x16x32_bf16 v[58:61], v[2:5], v[134:137], v[58:61]
	s_waitcnt lgkmcnt(0)
	v_mfma_f32_16x16x32_bf16 v[62:65], v[2:5], v[138:141], v[62:65]
	s_mov_b64 exec, s[70:71]
	ds_read_b128 v[6:9], v142 offset:11456
	s_mov_b64 exec, -1
	ds_read_b64_tr_b16 v[10:11], v143 offset:128
	ds_read_b64_tr_b16 v[12:13], v143 offset:1280
	ds_read_b64_tr_b16 v[14:15], v143 offset:160
	ds_read_b64_tr_b16 v[16:17], v143 offset:1312
	ds_read_b64_tr_b16 v[134:135], v143 offset:192
	ds_read_b64_tr_b16 v[136:137], v143 offset:1344
	ds_read_b64_tr_b16 v[138:139], v143 offset:224
	ds_read_b64_tr_b16 v[140:141], v143 offset:1376
	s_waitcnt lgkmcnt(6)
	v_mfma_f32_16x16x32_bf16 v[66:69], v[6:9], v[10:13], v[66:69]
	s_waitcnt lgkmcnt(4)
	v_mfma_f32_16x16x32_bf16 v[70:73], v[6:9], v[14:17], v[70:73]
	s_waitcnt lgkmcnt(2)
	v_mfma_f32_16x16x32_bf16 v[74:77], v[6:9], v[134:137], v[74:77]
	s_waitcnt lgkmcnt(0)
	v_mfma_f32_16x16x32_bf16 v[226:229], v[6:9], v[138:141], v[226:229]
	ds_read2_b32 v[126:127], v191 offset0:160 offset1:164
	ds_read2_b32 v[128:129], v191 offset0:168 offset1:172
	ds_read2_b32 v[130:131], v191 offset0:176 offset1:180
	ds_read2_b32 v[132:133], v191 offset0:184 offset1:188
	s_waitcnt vmcnt(8)
	ds_write_b128 v199, v[94:97] offset:0
	ds_write_b128 v199, v[98:101] offset:1152
	ds_write_b128 v199, v[102:105] offset:2304
	ds_write_b128 v199, v[106:109] offset:3456
	ds_write_b128 v199, v[110:113] offset:4608
	ds_write_b128 v199, v[114:117] offset:5760
	ds_write_b128 v199, v[118:121] offset:6912
	ds_write_b128 v199, v[122:125] offset:8064
	s_waitcnt lgkmcnt(8)
	v_lshl_add_u32 v126, v126, 8, v194
	v_lshl_add_u32 v127, v127, 8, v194
	v_lshl_add_u32 v128, v128, 8, v194
	v_lshl_add_u32 v129, v129, 8, v194
	v_lshl_add_u32 v130, v130, 8, v194
	v_lshl_add_u32 v131, v131, 8, v194
	v_lshl_add_u32 v132, v132, 8, v194
	v_lshl_add_u32 v133, v133, 8, v194
	global_load_dwordx4 v[94:97], v126, s[46:47]
	global_load_dwordx4 v[98:101], v127, s[46:47]
	global_load_dwordx4 v[102:105], v128, s[46:47]
	global_load_dwordx4 v[106:109], v129, s[46:47]
	global_load_dwordx4 v[110:113], v130, s[46:47]
	global_load_dwordx4 v[114:117], v131, s[46:47]
	global_load_dwordx4 v[118:121], v132, s[46:47]
	global_load_dwordx4 v[122:125], v133, s[46:47]
	s_mov_b64 exec, s[70:71]
	ds_read_b128 v[2:5], v142 offset:9408
	s_mov_b64 exec, -1
	ds_read_b64_tr_b16 v[10:11], v143 offset:0
	ds_read_b64_tr_b16 v[12:13], v143 offset:1152
	ds_read_b64_tr_b16 v[14:15], v143 offset:32
	ds_read_b64_tr_b16 v[16:17], v143 offset:1184
	ds_read_b64_tr_b16 v[134:135], v143 offset:64
	ds_read_b64_tr_b16 v[136:137], v143 offset:1216
	ds_read_b64_tr_b16 v[138:139], v143 offset:96
	ds_read_b64_tr_b16 v[140:141], v143 offset:1248
	s_waitcnt lgkmcnt(6)
	v_mfma_f32_16x16x32_bf16 v[50:53], v[2:5], v[10:13], v[50:53]
	s_waitcnt lgkmcnt(4)
	v_mfma_f32_16x16x32_bf16 v[54:57], v[2:5], v[14:17], v[54:57]
	s_waitcnt lgkmcnt(2)
	v_mfma_f32_16x16x32_bf16 v[58:61], v[2:5], v[134:137], v[58:61]
	s_waitcnt lgkmcnt(0)
	v_mfma_f32_16x16x32_bf16 v[62:65], v[2:5], v[138:141], v[62:65]
	s_mov_b64 exec, s[70:71]
	ds_read_b128 v[6:9], v142 offset:11520
	s_mov_b64 exec, -1
	ds_read_b64_tr_b16 v[10:11], v143 offset:128
	ds_read_b64_tr_b16 v[12:13], v143 offset:1280
	ds_read_b64_tr_b16 v[14:15], v143 offset:160
	ds_read_b64_tr_b16 v[16:17], v143 offset:1312
	ds_read_b64_tr_b16 v[134:135], v143 offset:192
	ds_read_b64_tr_b16 v[136:137], v143 offset:1344
	ds_read_b64_tr_b16 v[138:139], v143 offset:224
	ds_read_b64_tr_b16 v[140:141], v143 offset:1376
	s_waitcnt lgkmcnt(6)
	v_mfma_f32_16x16x32_bf16 v[66:69], v[6:9], v[10:13], v[66:69]
	s_waitcnt lgkmcnt(4)
	v_mfma_f32_16x16x32_bf16 v[70:73], v[6:9], v[14:17], v[70:73]
	s_waitcnt lgkmcnt(2)
	v_mfma_f32_16x16x32_bf16 v[74:77], v[6:9], v[134:137], v[74:77]
	s_waitcnt lgkmcnt(0)
	v_mfma_f32_16x16x32_bf16 v[226:229], v[6:9], v[138:141], v[226:229]
	ds_read2_b32 v[126:127], v191 offset0:192 offset1:196
	ds_read2_b32 v[128:129], v191 offset0:200 offset1:204
	ds_read2_b32 v[130:131], v191 offset0:208 offset1:212
	ds_read2_b32 v[132:133], v191 offset0:216 offset1:220
	s_waitcnt vmcnt(8)
	ds_write_b128 v199, v[18:21] offset:0
	ds_write_b128 v199, v[22:25] offset:1152
	ds_write_b128 v199, v[26:29] offset:2304
	ds_write_b128 v199, v[30:33] offset:3456
	ds_write_b128 v199, v[34:37] offset:4608
	ds_write_b128 v199, v[38:41] offset:5760
	ds_write_b128 v199, v[42:45] offset:6912
	ds_write_b128 v199, v[46:49] offset:8064
	s_waitcnt lgkmcnt(8)
	v_lshl_add_u32 v126, v126, 8, v194
	v_lshl_add_u32 v127, v127, 8, v194
	v_lshl_add_u32 v128, v128, 8, v194
	v_lshl_add_u32 v129, v129, 8, v194
	v_lshl_add_u32 v130, v130, 8, v194
	v_lshl_add_u32 v131, v131, 8, v194
	v_lshl_add_u32 v132, v132, 8, v194
	v_lshl_add_u32 v133, v133, 8, v194
	global_load_dwordx4 v[18:21], v126, s[46:47]
	global_load_dwordx4 v[22:25], v127, s[46:47]
	global_load_dwordx4 v[26:29], v128, s[46:47]
	global_load_dwordx4 v[30:33], v129, s[46:47]
	global_load_dwordx4 v[34:37], v130, s[46:47]
	global_load_dwordx4 v[38:41], v131, s[46:47]
	global_load_dwordx4 v[42:45], v132, s[46:47]
	global_load_dwordx4 v[46:49], v133, s[46:47]
	s_mov_b64 exec, s[70:71]
	ds_read_b128 v[2:5], v142 offset:9472
	s_mov_b64 exec, -1
	ds_read_b64_tr_b16 v[10:11], v143 offset:0
	ds_read_b64_tr_b16 v[12:13], v143 offset:1152
	ds_read_b64_tr_b16 v[14:15], v143 offset:32
	ds_read_b64_tr_b16 v[16:17], v143 offset:1184
	ds_read_b64_tr_b16 v[134:135], v143 offset:64
	ds_read_b64_tr_b16 v[136:137], v143 offset:1216
	ds_read_b64_tr_b16 v[138:139], v143 offset:96
	ds_read_b64_tr_b16 v[140:141], v143 offset:1248
	s_waitcnt lgkmcnt(6)
	v_mfma_f32_16x16x32_bf16 v[50:53], v[2:5], v[10:13], v[50:53]
	s_waitcnt lgkmcnt(4)
	v_mfma_f32_16x16x32_bf16 v[54:57], v[2:5], v[14:17], v[54:57]
	s_waitcnt lgkmcnt(2)
	v_mfma_f32_16x16x32_bf16 v[58:61], v[2:5], v[134:137], v[58:61]
	s_waitcnt lgkmcnt(0)
	v_mfma_f32_16x16x32_bf16 v[62:65], v[2:5], v[138:141], v[62:65]
	s_mov_b64 exec, s[70:71]
	ds_read_b128 v[6:9], v142 offset:11584
	s_mov_b64 exec, -1
	ds_read_b64_tr_b16 v[10:11], v143 offset:128
	ds_read_b64_tr_b16 v[12:13], v143 offset:1280
	ds_read_b64_tr_b16 v[14:15], v143 offset:160
	ds_read_b64_tr_b16 v[16:17], v143 offset:1312
	ds_read_b64_tr_b16 v[134:135], v143 offset:192
	ds_read_b64_tr_b16 v[136:137], v143 offset:1344
	ds_read_b64_tr_b16 v[138:139], v143 offset:224
	ds_read_b64_tr_b16 v[140:141], v143 offset:1376
	s_waitcnt lgkmcnt(6)
	v_mfma_f32_16x16x32_bf16 v[66:69], v[6:9], v[10:13], v[66:69]
	s_waitcnt lgkmcnt(4)
	v_mfma_f32_16x16x32_bf16 v[70:73], v[6:9], v[14:17], v[70:73]
	s_waitcnt lgkmcnt(2)
	v_mfma_f32_16x16x32_bf16 v[74:77], v[6:9], v[134:137], v[74:77]
	s_waitcnt lgkmcnt(0)
	v_mfma_f32_16x16x32_bf16 v[226:229], v[6:9], v[138:141], v[226:229]
	ds_read2_b32 v[126:127], v191 offset0:224 offset1:228
	ds_read2_b32 v[128:129], v191 offset0:232 offset1:236
	ds_read2_b32 v[130:131], v191 offset0:240 offset1:244
	ds_read2_b32 v[132:133], v191 offset0:248 offset1:252
	s_waitcnt vmcnt(8)
	ds_write_b128 v199, v[94:97] offset:0
	ds_write_b128 v199, v[98:101] offset:1152
	ds_write_b128 v199, v[102:105] offset:2304
	ds_write_b128 v199, v[106:109] offset:3456
	ds_write_b128 v199, v[110:113] offset:4608
	ds_write_b128 v199, v[114:117] offset:5760
	ds_write_b128 v199, v[118:121] offset:6912
	ds_write_b128 v199, v[122:125] offset:8064
	s_waitcnt lgkmcnt(8)
	v_lshl_add_u32 v126, v126, 8, v194
	v_lshl_add_u32 v127, v127, 8, v194
	v_lshl_add_u32 v128, v128, 8, v194
	v_lshl_add_u32 v129, v129, 8, v194
	v_lshl_add_u32 v130, v130, 8, v194
	v_lshl_add_u32 v131, v131, 8, v194
	v_lshl_add_u32 v132, v132, 8, v194
	v_lshl_add_u32 v133, v133, 8, v194
	global_load_dwordx4 v[94:97], v126, s[46:47]
	global_load_dwordx4 v[98:101], v127, s[46:47]
	global_load_dwordx4 v[102:105], v128, s[46:47]
	global_load_dwordx4 v[106:109], v129, s[46:47]
	global_load_dwordx4 v[110:113], v130, s[46:47]
	global_load_dwordx4 v[114:117], v131, s[46:47]
	global_load_dwordx4 v[118:121], v132, s[46:47]
	global_load_dwordx4 v[122:125], v133, s[46:47]
	s_mov_b64 exec, s[70:71]
	ds_read_b128 v[2:5], v142 offset:9536
	s_mov_b64 exec, -1
	ds_read_b64_tr_b16 v[10:11], v143 offset:0
	ds_read_b64_tr_b16 v[12:13], v143 offset:1152
	ds_read_b64_tr_b16 v[14:15], v143 offset:32
	ds_read_b64_tr_b16 v[16:17], v143 offset:1184
	ds_read_b64_tr_b16 v[134:135], v143 offset:64
	ds_read_b64_tr_b16 v[136:137], v143 offset:1216
	ds_read_b64_tr_b16 v[138:139], v143 offset:96
	ds_read_b64_tr_b16 v[140:141], v143 offset:1248
	s_waitcnt lgkmcnt(6)
	v_mfma_f32_16x16x32_bf16 v[50:53], v[2:5], v[10:13], v[50:53]
	s_waitcnt lgkmcnt(4)
	v_mfma_f32_16x16x32_bf16 v[54:57], v[2:5], v[14:17], v[54:57]
	s_waitcnt lgkmcnt(2)
	v_mfma_f32_16x16x32_bf16 v[58:61], v[2:5], v[134:137], v[58:61]
	s_waitcnt lgkmcnt(0)
	v_mfma_f32_16x16x32_bf16 v[62:65], v[2:5], v[138:141], v[62:65]
	s_mov_b64 exec, s[70:71]
	ds_read_b128 v[6:9], v142 offset:11648
	s_mov_b64 exec, -1
	ds_read_b64_tr_b16 v[10:11], v143 offset:128
	ds_read_b64_tr_b16 v[12:13], v143 offset:1280
	ds_read_b64_tr_b16 v[14:15], v143 offset:160
	ds_read_b64_tr_b16 v[16:17], v143 offset:1312
	ds_read_b64_tr_b16 v[134:135], v143 offset:192
	ds_read_b64_tr_b16 v[136:137], v143 offset:1344
	ds_read_b64_tr_b16 v[138:139], v143 offset:224
	ds_read_b64_tr_b16 v[140:141], v143 offset:1376
	s_waitcnt lgkmcnt(6)
	v_mfma_f32_16x16x32_bf16 v[66:69], v[6:9], v[10:13], v[66:69]
	s_waitcnt lgkmcnt(4)
	v_mfma_f32_16x16x32_bf16 v[70:73], v[6:9], v[14:17], v[70:73]
	s_waitcnt lgkmcnt(2)
	v_mfma_f32_16x16x32_bf16 v[74:77], v[6:9], v[134:137], v[74:77]
	s_waitcnt lgkmcnt(0)
	v_mfma_f32_16x16x32_bf16 v[226:229], v[6:9], v[138:141], v[226:229]
	s_waitcnt vmcnt(8)
	ds_write_b128 v199, v[18:21] offset:0
	ds_write_b128 v199, v[22:25] offset:1152
	ds_write_b128 v199, v[26:29] offset:2304
	ds_write_b128 v199, v[30:33] offset:3456
	ds_write_b128 v199, v[34:37] offset:4608
	ds_write_b128 v199, v[38:41] offset:5760
	ds_write_b128 v199, v[42:45] offset:6912
	ds_write_b128 v199, v[46:49] offset:8064
	s_mov_b64 exec, s[70:71]
	ds_read_b128 v[2:5], v142 offset:9600
	s_mov_b64 exec, -1
	ds_read_b64_tr_b16 v[10:11], v143 offset:0
	ds_read_b64_tr_b16 v[12:13], v143 offset:1152
	ds_read_b64_tr_b16 v[14:15], v143 offset:32
	ds_read_b64_tr_b16 v[16:17], v143 offset:1184
	ds_read_b64_tr_b16 v[134:135], v143 offset:64
	ds_read_b64_tr_b16 v[136:137], v143 offset:1216
	ds_read_b64_tr_b16 v[138:139], v143 offset:96
	ds_read_b64_tr_b16 v[140:141], v143 offset:1248
	s_waitcnt lgkmcnt(6)
	v_mfma_f32_16x16x32_bf16 v[50:53], v[2:5], v[10:13], v[50:53]
	s_waitcnt lgkmcnt(4)
	v_mfma_f32_16x16x32_bf16 v[54:57], v[2:5], v[14:17], v[54:57]
	s_waitcnt lgkmcnt(2)
	v_mfma_f32_16x16x32_bf16 v[58:61], v[2:5], v[134:137], v[58:61]
	s_waitcnt lgkmcnt(0)
	v_mfma_f32_16x16x32_bf16 v[62:65], v[2:5], v[138:141], v[62:65]
	s_mov_b64 exec, s[70:71]
	ds_read_b128 v[6:9], v142 offset:11712
	s_mov_b64 exec, -1
	ds_read_b64_tr_b16 v[10:11], v143 offset:128
	ds_read_b64_tr_b16 v[12:13], v143 offset:1280
	ds_read_b64_tr_b16 v[14:15], v143 offset:160
	ds_read_b64_tr_b16 v[16:17], v143 offset:1312
	ds_read_b64_tr_b16 v[134:135], v143 offset:192
	ds_read_b64_tr_b16 v[136:137], v143 offset:1344
	ds_read_b64_tr_b16 v[138:139], v143 offset:224
	ds_read_b64_tr_b16 v[140:141], v143 offset:1376
	s_waitcnt lgkmcnt(6)
	v_mfma_f32_16x16x32_bf16 v[66:69], v[6:9], v[10:13], v[66:69]
	s_waitcnt lgkmcnt(4)
	v_mfma_f32_16x16x32_bf16 v[70:73], v[6:9], v[14:17], v[70:73]
	s_waitcnt lgkmcnt(2)
	v_mfma_f32_16x16x32_bf16 v[74:77], v[6:9], v[134:137], v[74:77]
	s_waitcnt lgkmcnt(0)
	v_mfma_f32_16x16x32_bf16 v[226:229], v[6:9], v[138:141], v[226:229]
	s_waitcnt vmcnt(0)
	ds_write_b128 v199, v[94:97] offset:0
	ds_write_b128 v199, v[98:101] offset:1152
	ds_write_b128 v199, v[102:105] offset:2304
	ds_write_b128 v199, v[106:109] offset:3456
	ds_write_b128 v199, v[110:113] offset:4608
	ds_write_b128 v199, v[114:117] offset:5760
	ds_write_b128 v199, v[118:121] offset:6912
	ds_write_b128 v199, v[122:125] offset:8064
	s_mov_b64 exec, s[70:71]
	ds_read_b128 v[2:5], v142 offset:9664
	s_mov_b64 exec, -1
	ds_read_b64_tr_b16 v[10:11], v143 offset:0
	ds_read_b64_tr_b16 v[12:13], v143 offset:1152
	ds_read_b64_tr_b16 v[14:15], v143 offset:32
	ds_read_b64_tr_b16 v[16:17], v143 offset:1184
	ds_read_b64_tr_b16 v[134:135], v143 offset:64
	ds_read_b64_tr_b16 v[136:137], v143 offset:1216
	ds_read_b64_tr_b16 v[138:139], v143 offset:96
	ds_read_b64_tr_b16 v[140:141], v143 offset:1248
	s_waitcnt lgkmcnt(6)
	v_mfma_f32_16x16x32_bf16 v[50:53], v[2:5], v[10:13], v[50:53]
	s_waitcnt lgkmcnt(4)
	v_mfma_f32_16x16x32_bf16 v[54:57], v[2:5], v[14:17], v[54:57]
	s_waitcnt lgkmcnt(2)
	v_mfma_f32_16x16x32_bf16 v[58:61], v[2:5], v[134:137], v[58:61]
	s_waitcnt lgkmcnt(0)
	v_mfma_f32_16x16x32_bf16 v[62:65], v[2:5], v[138:141], v[62:65]
	s_mov_b64 exec, s[70:71]
	ds_read_b128 v[6:9], v142 offset:11776
	s_mov_b64 exec, -1
	ds_read_b64_tr_b16 v[10:11], v143 offset:128
	ds_read_b64_tr_b16 v[12:13], v143 offset:1280
	ds_read_b64_tr_b16 v[14:15], v143 offset:160
	ds_read_b64_tr_b16 v[16:17], v143 offset:1312
	ds_read_b64_tr_b16 v[134:135], v143 offset:192
	ds_read_b64_tr_b16 v[136:137], v143 offset:1344
	ds_read_b64_tr_b16 v[138:139], v143 offset:224
	ds_read_b64_tr_b16 v[140:141], v143 offset:1376
	s_waitcnt lgkmcnt(6)
	v_mfma_f32_16x16x32_bf16 v[66:69], v[6:9], v[10:13], v[66:69]
	s_waitcnt lgkmcnt(4)
	v_mfma_f32_16x16x32_bf16 v[70:73], v[6:9], v[14:17], v[70:73]
	s_waitcnt lgkmcnt(2)
	v_mfma_f32_16x16x32_bf16 v[74:77], v[6:9], v[134:137], v[74:77]
	s_waitcnt lgkmcnt(0)
	v_mfma_f32_16x16x32_bf16 v[226:229], v[6:9], v[138:141], v[226:229]
	s_nop 7
	s_nop 1
	v_lshl_add_u32 v144, v202, 1, s55
	s_mov_b64 exec, 0xffff
	v_mul_f32_e32 v50, s62, v50
	v_mul_f32_e32 v51, s63, v51
	v_mul_f32_e32 v52, s64, v52
	v_mul_f32_e32 v53, s65, v53
	v_cvt_pk_bf16_f32 v50, v50, v50
	v_cvt_pk_bf16_f32 v51, v51, v51
	v_cvt_pk_bf16_f32 v52, v52, v52
	v_cvt_pk_bf16_f32 v53, v53, v53
	ds_write_b16 v144, v50 offset:0
	ds_write_b16 v144, v51 offset:128
	ds_write_b16 v144, v52 offset:256
	ds_write_b16 v144, v53 offset:384
	v_mul_f32_e32 v54, s62, v54
	v_mul_f32_e32 v55, s63, v55
	v_mul_f32_e32 v56, s64, v56
	v_mul_f32_e32 v57, s65, v57
	v_cvt_pk_bf16_f32 v54, v54, v54
	v_cvt_pk_bf16_f32 v55, v55, v55
	v_cvt_pk_bf16_f32 v56, v56, v56
	v_cvt_pk_bf16_f32 v57, v57, v57
	ds_write_b16 v144, v54 offset:32
	ds_write_b16 v144, v55 offset:160
	ds_write_b16 v144, v56 offset:288
	ds_write_b16 v144, v57 offset:416
	v_mul_f32_e32 v58, s62, v58
	v_mul_f32_e32 v59, s63, v59
	v_mul_f32_e32 v60, s64, v60
	v_mul_f32_e32 v61, s65, v61
	v_cvt_pk_bf16_f32 v58, v58, v58
	v_cvt_pk_bf16_f32 v59, v59, v59
	v_cvt_pk_bf16_f32 v60, v60, v60
	v_cvt_pk_bf16_f32 v61, v61, v61
	ds_write_b16 v144, v58 offset:64
	ds_write_b16 v144, v59 offset:192
	ds_write_b16 v144, v60 offset:320
	ds_write_b16 v144, v61 offset:448
	v_mul_f32_e32 v62, s62, v62
	v_mul_f32_e32 v63, s63, v63
	v_mul_f32_e32 v64, s64, v64
	v_mul_f32_e32 v65, s65, v65
	v_cvt_pk_bf16_f32 v62, v62, v62
	v_cvt_pk_bf16_f32 v63, v63, v63
	v_cvt_pk_bf16_f32 v64, v64, v64
	v_cvt_pk_bf16_f32 v65, v65, v65
	ds_write_b16 v144, v62 offset:96
	ds_write_b16 v144, v63 offset:224
	ds_write_b16 v144, v64 offset:352
	ds_write_b16 v144, v65 offset:480
	v_mul_f32_e32 v66, s66, v66
	v_mul_f32_e32 v67, s67, v67
	v_mul_f32_e32 v68, s68, v68
	v_mul_f32_e32 v69, s69, v69
	v_cvt_pk_bf16_f32 v66, v66, v66
	v_cvt_pk_bf16_f32 v67, v67, v67
	v_cvt_pk_bf16_f32 v68, v68, v68
	v_cvt_pk_bf16_f32 v69, v69, v69
	ds_write_b16 v144, v66 offset:512
	ds_write_b16 v144, v67 offset:640
	ds_write_b16 v144, v68 offset:768
	ds_write_b16 v144, v69 offset:896
	v_mul_f32_e32 v70, s66, v70
	v_mul_f32_e32 v71, s67, v71
	v_mul_f32_e32 v72, s68, v72
	v_mul_f32_e32 v73, s69, v73
	v_cvt_pk_bf16_f32 v70, v70, v70
	v_cvt_pk_bf16_f32 v71, v71, v71
	v_cvt_pk_bf16_f32 v72, v72, v72
	v_cvt_pk_bf16_f32 v73, v73, v73
	ds_write_b16 v144, v70 offset:544
	ds_write_b16 v144, v71 offset:672
	ds_write_b16 v144, v72 offset:800
	ds_write_b16 v144, v73 offset:928
	v_mul_f32_e32 v74, s66, v74
	v_mul_f32_e32 v75, s67, v75
	v_mul_f32_e32 v76, s68, v76
	v_mul_f32_e32 v77, s69, v77
	v_cvt_pk_bf16_f32 v74, v74, v74
	v_cvt_pk_bf16_f32 v75, v75, v75
	v_cvt_pk_bf16_f32 v76, v76, v76
	v_cvt_pk_bf16_f32 v77, v77, v77
	ds_write_b16 v144, v74 offset:576
	ds_write_b16 v144, v75 offset:704
	ds_write_b16 v144, v76 offset:832
	ds_write_b16 v144, v77 offset:960
	v_mul_f32_e32 v226, s66, v226
	v_mul_f32_e32 v227, s67, v227
	v_mul_f32_e32 v228, s68, v228
	v_mul_f32_e32 v229, s69, v229
	v_cvt_pk_bf16_f32 v226, v226, v226
	v_cvt_pk_bf16_f32 v227, v227, v227
	v_cvt_pk_bf16_f32 v228, v228, v228
	v_cvt_pk_bf16_f32 v229, v229, v229
	ds_write_b16 v144, v226 offset:608
	ds_write_b16 v144, v227 offset:736
	ds_write_b16 v144, v228 offset:864
	ds_write_b16 v144, v229 offset:992
	s_mov_b64 exec, -1
	v_lshlrev_b32_e32 v142, 4, v219
	v_add_u32_e32 v143, s55, v142
	s_waitcnt lgkmcnt(0)
	ds_read_b128 v[10:13], v143
	s_waitcnt lgkmcnt(0)
	global_store_dwordx4 v142, v[10:13], s[50:51]
	s_mov_b64 s[0:1], exec
	s_branch .LBB0_317
.Lhop_1587:
	s_branch .LBB0_1587
.Lfa_skip:
	v_add_u32_e32 v38, v138, v237
	v_ashrrev_i32_e32 v131, 31, v130
	v_lshlrev_b64 v[34:35], 19, v[130:131]
	s_mov_b64 s[2:3], 0
	v_ashrrev_i32_e32 v39, 31, v38
	v_lshlrev_b32_e32 v0, 1, v216
	v_lshlrev_b32_e32 v36, 1, v214
	s_and_saveexec_b64 s[0:1], s[18:19]
	s_xor_b64 s[18:19], exec, s[0:1]
	s_cbranch_execz .LBB0_702
	v_readlane_b32 s36, v251, 1
	v_readlane_b32 s50, v251, 15
	v_readlane_b32 s51, v251, 16
	s_mov_b64 s[20:21], s[50:51]
	v_lshlrev_b64 v[224:225], 10, v[38:39]
	v_mov_b32_e32 v37, v1
	v_lshl_add_u64 v[18:19], s[20:21], 0, v[224:225]
	v_lshl_add_u64 v[18:19], v[18:19], 0, v[0:1]
	v_lshl_add_u64 v[18:19], v[18:19], 0, v[36:37]
	s_mov_b64 s[0:1], 0x6080000
	v_lshl_add_u64 v[36:37], v[18:19], 0, s[0:1]
	v_mov_b32_e32 v18, 0
	v_mov_b32_e32 v22, 0
	s_waitcnt lgkmcnt(0)
	v_mov_b32_e32 v23, 0
	v_mov_b32_e32 v24, 0
	v_mov_b32_e32 v25, 0
	v_readlane_b32 s37, v251, 2
	v_readlane_b32 s38, v251, 3
	v_readlane_b32 s39, v251, 4
	v_readlane_b32 s40, v251, 5
	v_readlane_b32 s41, v251, 6
	v_readlane_b32 s42, v251, 7
	v_readlane_b32 s43, v251, 8
	v_readlane_b32 s44, v251, 9
	v_readlane_b32 s45, v251, 10
	v_readlane_b32 s46, v251, 11
	v_readlane_b32 s47, v251, 12
	v_readlane_b32 s48, v251, 13
	v_readlane_b32 s49, v251, 14
	s_and_saveexec_b64 s[0:1], s[16:17]
	s_cbranch_execz .LBB0_686
	flat_load_dwordx4 v[22:25], v[36:37]

	.amdhsa_kernel _Z10fwd_kernel6Params
		.amdhsa_group_segment_fixed_size 20480
		.amdhsa_private_segment_fixed_size 0
		.amdhsa_kernarg_size 456
		.amdhsa_user_sgpr_count 2
		.amdhsa_user_sgpr_dispatch_ptr 0
		.amdhsa_user_sgpr_queue_ptr 0
		.amdhsa_user_sgpr_kernarg_segment_ptr 1
		.amdhsa_user_sgpr_dispatch_id 0
		.amdhsa_user_sgpr_kernarg_preload_length 0
		.amdhsa_user_sgpr_kernarg_preload_offset 0
		.amdhsa_user_sgpr_private_segment_size 0
		.amdhsa_uses_dynamic_stack 0
		.amdhsa_enable_private_segment 0
		.amdhsa_system_sgpr_workgroup_id_x 1
		.amdhsa_system_sgpr_workgroup_id_y 0
		.amdhsa_system_sgpr_workgroup_id_z 0
		.amdhsa_system_sgpr_workgroup_info 0
		.amdhsa_system_vgpr_workitem_id 2
		.amdhsa_next_free_vgpr 256
		.amdhsa_next_free_sgpr 100
		.amdhsa_accum_offset 256
		.amdhsa_reserve_vcc 1
		.amdhsa_float_round_mode_32 0
		.amdhsa_float_round_mode_16_64 0
		.amdhsa_float_denorm_mode_32 3
		.amdhsa_float_denorm_mode_16_64 3
		.amdhsa_dx10_clamp 1
		.amdhsa_ieee_mode 1
		.amdhsa_fp16_overflow 0
		.amdhsa_tg_split 0
		.amdhsa_exception_fp_ieee_invalid_op 0
		.amdhsa_exception_fp_denorm_src 0
		.amdhsa_exception_fp_ieee_div_zero 0
		.amdhsa_exception_fp_ieee_overflow 0
		.amdhsa_exception_fp_ieee_underflow 0
		.amdhsa_exception_fp_ieee_inexact 0
		.amdhsa_exception_int_div_zero 0
	.end_amdhsa_kernel

amdhsa.kernels:
  - .agpr_count:     0
    .args:
      - .offset:         0
        .size:           200
        .value_kind:     by_value
      - .offset:         200
        .size:           4
        .value_kind:     hidden_block_count_x
      - .offset:         204
        .size:           4
        .value_kind:     hidden_block_count_y
      - .offset:         208
        .size:           4
        .value_kind:     hidden_block_count_z
      - .offset:         212
        .size:           2
        .value_kind:     hidden_group_size_x
      - .offset:         214
        .size:           2
        .value_kind:     hidden_group_size_y
      - .offset:         216
        .size:           2
        .value_kind:     hidden_group_size_z
      - .offset:         218
        .size:           2
        .value_kind:     hidden_remainder_x
      - .offset:         220
        .size:           2
        .value_kind:     hidden_remainder_y
      - .offset:         222
        .size:           2
        .value_kind:     hidden_remainder_z
      - .offset:         240
        .size:           8
        .value_kind:     hidden_global_offset_x
      - .offset:         248
        .size:           8
        .value_kind:     hidden_global_offset_y
      - .offset:         256
        .size:           8
        .value_kind:     hidden_global_offset_z
      - .offset:         264
        .size:           2
        .value_kind:     hidden_grid_dims
      - .offset:         288
        .size:           8
        .value_kind:     hidden_multigrid_sync_arg
      - .offset:         320
        .size:           4
        .value_kind:     hidden_dynamic_lds_size
    .group_segment_fixed_size: 20480
    .kernarg_segment_align: 8
    .kernarg_segment_size: 456
    .language:       OpenCL C
    .language_version:
      - 2
      - 0
    .max_flat_workgroup_size: 512
    .name:           _Z10fwd_kernel6Params
    .private_segment_fixed_size: 0
    .sgpr_count:     106
    .sgpr_spill_count: 389
    .symbol:         _Z10fwd_kernel6Params.kd
    .uniform_work_group_size: 1
    .uses_dynamic_stack: false
    .vgpr_count:     256
    .vgpr_spill_count: 0
    .wavefront_size: 64
